# stacked: static s_setprio 1 for waves 4-7 around GEMM k-loops (toggles removed) + top-k vmcnt(7) counted wait, on the previous best
# baseline (speedup 1.0000x reference)
.LBB0_126:
	s_waitcnt vmcnt(0)
	v_mov_b32_e32 v0, 0
	v_lshl_add_u64 v[142:143], v[138:139], 0, s[48:49]
	v_lshl_add_u64 v[144:145], v[138:139], 0, s[38:39]
	s_mov_b32 s20, 0
	s_mov_b64 s[48:49], 0
	v_mov_b32_e32 v1, v0
	v_mov_b32_e32 v2, v0
	v_mov_b32_e32 v3, v0
	v_mov_b32_e32 v4, v0
	v_mov_b32_e32 v5, v0
	v_mov_b32_e32 v6, v0
	v_mov_b32_e32 v7, v0
	v_mov_b32_e32 v8, v0
	v_mov_b32_e32 v9, v0
	v_mov_b32_e32 v10, v0
	v_mov_b32_e32 v11, v0
	v_mov_b32_e32 v12, v0
	v_mov_b32_e32 v13, v0
	v_mov_b32_e32 v14, v0
	v_mov_b32_e32 v15, v0
	v_mov_b32_e32 v16, v0
	v_mov_b32_e32 v17, v0
	v_mov_b32_e32 v18, v0
	v_mov_b32_e32 v19, v0
	v_mov_b32_e32 v20, v0
	v_mov_b32_e32 v21, v0
	v_mov_b32_e32 v22, v0
	v_mov_b32_e32 v23, v0
	v_mov_b32_e32 v24, v0
	v_mov_b32_e32 v25, v0
	v_mov_b32_e32 v26, v0
	v_mov_b32_e32 v27, v0
	v_mov_b32_e32 v28, v0
	v_mov_b32_e32 v29, v0
	v_mov_b32_e32 v30, v0
	v_mov_b32_e32 v31, v0
	v_mov_b32_e32 v64, v0
	v_mov_b32_e32 v65, v0
	v_mov_b32_e32 v66, v0
	v_mov_b32_e32 v67, v0
	v_mov_b32_e32 v68, v0
	v_mov_b32_e32 v69, v0
	v_mov_b32_e32 v70, v0
	v_mov_b32_e32 v71, v0
	v_mov_b32_e32 v72, v0
	v_mov_b32_e32 v73, v0
	v_mov_b32_e32 v74, v0
	v_mov_b32_e32 v75, v0
	v_mov_b32_e32 v76, v0
	v_mov_b32_e32 v77, v0
	v_mov_b32_e32 v78, v0
	v_mov_b32_e32 v79, v0
	v_mov_b32_e32 v80, v0
	v_mov_b32_e32 v81, v0
	v_mov_b32_e32 v82, v0
	v_mov_b32_e32 v83, v0
	v_mov_b32_e32 v84, v0
	v_mov_b32_e32 v85, v0
	v_mov_b32_e32 v86, v0
	v_mov_b32_e32 v87, v0
	v_mov_b32_e32 v88, v0
	v_mov_b32_e32 v89, v0
	v_mov_b32_e32 v90, v0
	v_mov_b32_e32 v91, v0
	v_mov_b32_e32 v92, v0
	v_mov_b32_e32 v93, v0
	v_mov_b32_e32 v94, v0
	v_mov_b32_e32 v95, v0
	v_mov_b32_e32 v32, v0
	v_mov_b32_e32 v33, v0
	v_mov_b32_e32 v34, v0
	v_mov_b32_e32 v35, v0
	v_mov_b32_e32 v36, v0
	v_mov_b32_e32 v37, v0
	v_mov_b32_e32 v38, v0
	v_mov_b32_e32 v39, v0
	v_mov_b32_e32 v40, v0
	v_mov_b32_e32 v41, v0
	v_mov_b32_e32 v42, v0
	v_mov_b32_e32 v43, v0
	v_mov_b32_e32 v44, v0
	v_mov_b32_e32 v45, v0
	v_mov_b32_e32 v46, v0
	v_mov_b32_e32 v47, v0
	v_mov_b32_e32 v48, v0
	v_mov_b32_e32 v49, v0
	v_mov_b32_e32 v50, v0
	v_mov_b32_e32 v51, v0
	v_mov_b32_e32 v52, v0
	v_mov_b32_e32 v53, v0
	v_mov_b32_e32 v54, v0
	v_mov_b32_e32 v55, v0
	v_mov_b32_e32 v56, v0
	v_mov_b32_e32 v57, v0
	v_mov_b32_e32 v58, v0
	v_mov_b32_e32 v59, v0
	v_mov_b32_e32 v60, v0
	v_mov_b32_e32 v61, v0
	v_mov_b32_e32 v62, v0
	v_mov_b32_e32 v63, v0
	v_mov_b32_e32 v96, v0
	v_mov_b32_e32 v97, v0
	v_mov_b32_e32 v98, v0
	v_mov_b32_e32 v99, v0
	v_mov_b32_e32 v100, v0
	v_mov_b32_e32 v101, v0
	v_mov_b32_e32 v102, v0
	v_mov_b32_e32 v103, v0
	v_mov_b32_e32 v104, v0
	v_mov_b32_e32 v105, v0
	v_mov_b32_e32 v106, v0
	v_mov_b32_e32 v107, v0
	v_mov_b32_e32 v108, v0
	v_mov_b32_e32 v109, v0
	v_mov_b32_e32 v110, v0
	v_mov_b32_e32 v111, v0
	v_mov_b32_e32 v112, v0
	v_mov_b32_e32 v113, v0
	v_mov_b32_e32 v114, v0
	v_mov_b32_e32 v115, v0
	v_mov_b32_e32 v116, v0
	v_mov_b32_e32 v117, v0
	v_mov_b32_e32 v118, v0
	v_mov_b32_e32 v119, v0
	v_mov_b32_e32 v120, v0
	v_mov_b32_e32 v121, v0
	v_mov_b32_e32 v122, v0
	v_mov_b32_e32 v123, v0
	v_mov_b32_e32 v124, v0
	v_mov_b32_e32 v125, v0
	v_mov_b32_e32 v126, v0
	v_mov_b32_e32 v127, v0
	s_waitcnt vmcnt(0) lgkmcnt(0)
	v_readfirstlane_b32 vcc_lo, v135
	s_bitcmp1_b32 vcc_lo, 8
	s_cbranch_scc0 .Lprio_skip0
	s_setprio 1
.Lprio_skip0:
	s_barrier
	s_branch .LBB0_128
.LBB0_127:
	v_add_u32_e32 v210, s21, v157
	v_add3_u32 v206, v210, v152, v153
	v_add3_u32 v222, v210, v154, v153
	ds_read_b128 v[146:149], v206 offset:32768
	ds_read_b128 v[206:209], v206 offset:36864
	ds_read_b128 v[210:213], v222
	ds_read_b128 v[214:217], v222 offset:4096
	ds_read_b128 v[218:221], v222 offset:8192
	ds_read_b128 v[222:225], v222 offset:12288
	s_waitcnt lgkmcnt(3)
	v_mfma_f32_32x32x16_bf16 v[112:127], v[146:149], v[210:213], v[112:127]
	s_waitcnt lgkmcnt(2)
	v_mfma_f32_32x32x16_bf16 v[96:111], v[146:149], v[214:217], v[96:111]
	s_waitcnt lgkmcnt(1)
	v_mfma_f32_32x32x16_bf16 v[48:63], v[146:149], v[218:221], v[48:63]
	s_waitcnt lgkmcnt(0)
	v_mfma_f32_32x32x16_bf16 v[32:47], v[146:149], v[222:225], v[32:47]
	v_mfma_f32_32x32x16_bf16 v[80:95], v[206:209], v[210:213], v[80:95]
	v_mfma_f32_32x32x16_bf16 v[64:79], v[206:209], v[214:217], v[64:79]
	v_mfma_f32_32x32x16_bf16 v[16:31], v[206:209], v[218:221], v[16:31]
	v_mfma_f32_32x32x16_bf16 v[0:15], v[206:209], v[222:225], v[0:15]
	s_waitcnt vmcnt(0)
	s_add_u32 s48, s48, 0x80
	s_addc_u32 s49, s49, 0
	s_cmpk_eq_i32 s48, 0x800
	s_waitcnt vmcnt(0)
	s_barrier
	s_cbranch_scc1 .LBB0_134
.LBB0_128:
	s_cmpk_lg_i32 s48, 0x780
	s_cselect_b64 s[50:51], -1, 0
	s_and_b32 s21, s20, 0x10000
	s_add_i32 s21, s21, 0
	v_add_u32_e32 v146, s21, v151
	v_add3_u32 v147, v146, v152, v153
	v_add3_u32 v146, v146, v154, v153
	ds_read_b128 v[206:209], v147 offset:32768
	ds_read_b128 v[210:213], v147 offset:36864
	ds_read_b128 v[214:217], v146
	ds_read_b128 v[218:221], v146 offset:4096
	ds_read_b128 v[222:225], v146 offset:8192
	ds_read_b128 v[226:229], v146 offset:12288
	s_add_i32 s20, s20, 0x10000
	s_and_b32 s24, s20, 0x10000
	v_lshl_add_u64 v[148:149], v[144:145], 0, s[48:49]
	s_cmpk_eq_i32 s48, 0x780
	s_waitcnt lgkmcnt(3)
	v_mfma_f32_32x32x16_bf16 v[112:127], v[206:209], v[214:217], v[112:127]
	s_waitcnt lgkmcnt(2)
	v_mfma_f32_32x32x16_bf16 v[96:111], v[206:209], v[218:221], v[96:111]
	s_waitcnt lgkmcnt(1)
	v_mfma_f32_32x32x16_bf16 v[48:63], v[206:209], v[222:225], v[48:63]
	s_waitcnt lgkmcnt(0)
	v_mfma_f32_32x32x16_bf16 v[32:47], v[206:209], v[226:229], v[32:47]
	v_mfma_f32_32x32x16_bf16 v[80:95], v[210:213], v[214:217], v[80:95]
	v_mfma_f32_32x32x16_bf16 v[64:79], v[210:213], v[218:221], v[64:79]
	v_mfma_f32_32x32x16_bf16 v[16:31], v[210:213], v[222:225], v[16:31]
	v_mfma_f32_32x32x16_bf16 v[0:15], v[210:213], v[226:229], v[0:15]
	v_add_u32_e32 v206, s24, v150
	s_cbranch_scc1 .LBB0_130
	s_mov_b64 s[24:25], 0x8bac080
	v_lshl_add_u64 v[146:147], v[148:149], 0, s[24:25]
	s_mov_b64 s[24:25], 0x8b8c080
	v_lshl_add_u64 v[208:209], v[148:149], 0, s[24:25]
	s_mov_b64 s[24:25], 0x8b6c080
	v_lshl_add_u64 v[210:211], v[148:149], 0, s[24:25]
	v_readfirstlane_b32 s24, v206
	v_add_u32_e32 v207, 0x2000, v206
	s_mov_b32 m0, s24
	v_readfirstlane_b32 s24, v207
	v_add_u32_e32 v207, 0x4000, v206
	global_load_lds_dwordx4 v[210:211], off
	s_mov_b32 m0, s24
	v_readfirstlane_b32 s24, v207
	global_load_lds_dwordx4 v[208:209], off
	s_mov_b32 m0, s24
	s_movk_i32 s25, 0x1000
	global_load_lds_dwordx4 v[146:147], off
.LBB0_130:
	v_lshl_add_u64 v[146:147], v[142:143], 0, s[48:49]
	v_add_u32_e32 v207, s21, v155
	v_add3_u32 v212, v207, v152, v153
	v_add3_u32 v207, v207, v154, v153
	ds_read_b128 v[208:211], v212 offset:32768
	ds_read_b128 v[212:215], v212 offset:36864
	ds_read_b128 v[216:219], v207
	ds_read_b128 v[220:223], v207 offset:4096
	ds_read_b128 v[224:227], v207 offset:8192
	ds_read_b128 v[228:231], v207 offset:12288
	s_waitcnt lgkmcnt(3)
	v_mfma_f32_32x32x16_bf16 v[112:127], v[208:211], v[216:219], v[112:127]
	s_waitcnt lgkmcnt(2)
	v_mfma_f32_32x32x16_bf16 v[96:111], v[208:211], v[220:223], v[96:111]
	s_waitcnt lgkmcnt(1)
	v_mfma_f32_32x32x16_bf16 v[48:63], v[208:211], v[224:227], v[48:63]
	s_waitcnt lgkmcnt(0)
	v_mfma_f32_32x32x16_bf16 v[32:47], v[208:211], v[228:231], v[32:47]
	v_mfma_f32_32x32x16_bf16 v[80:95], v[212:215], v[216:219], v[80:95]
	v_mfma_f32_32x32x16_bf16 v[64:79], v[212:215], v[220:223], v[64:79]
	v_mfma_f32_32x32x16_bf16 v[16:31], v[212:215], v[224:227], v[16:31]
	v_mfma_f32_32x32x16_bf16 v[0:15], v[212:215], v[228:231], v[0:15]
	v_cndmask_b32_e64 v207, 0, 1, s[50:51]
	v_cmp_ne_u32_e64 s[38:39], 1, v207
	s_andn2_b64 vcc, exec, s[50:51]
	s_cbranch_vccnz .LBB0_132
	s_mov_b64 s[24:25], 0x8bcc080
	v_lshl_add_u64 v[148:149], v[148:149], 0, s[24:25]
	s_mov_b64 s[24:25], 0x1c00080
	v_lshl_add_u64 v[208:209], v[146:147], 0, s[24:25]
	s_mov_b64 s[24:25], 0x1c20080
	v_add_u32_e32 v207, 0x6000, v206
	v_lshl_add_u64 v[210:211], v[146:147], 0, s[24:25]
	v_readfirstlane_b32 s24, v207
	s_mov_b32 m0, s24
	s_movk_i32 s25, 0x1000
	global_load_lds_dwordx4 v[148:149], off
	v_add_u32_e32 v148, 0x8000, v206
	s_nop 0
	v_readfirstlane_b32 s24, v148
	v_add_u32_e32 v148, 0xa000, v206
	s_mov_b32 m0, s24
	v_readfirstlane_b32 s24, v148
	global_load_lds_dwordx4 v[208:209], off
	s_mov_b32 m0, s24
	s_nop 0
	global_load_lds_dwordx4 v[210:211], off
.LBB0_132:
	v_add_u32_e32 v148, s21, v156
	v_add3_u32 v149, v148, v152, v153
	v_add3_u32 v148, v148, v154, v153
	ds_read_b128 v[208:211], v149 offset:32768
	ds_read_b128 v[212:215], v149 offset:36864
	ds_read_b128 v[216:219], v148
	ds_read_b128 v[220:223], v148 offset:4096
	ds_read_b128 v[224:227], v148 offset:8192
	ds_read_b128 v[228:231], v148 offset:12288
	s_waitcnt lgkmcnt(3)
	v_mfma_f32_32x32x16_bf16 v[112:127], v[208:211], v[216:219], v[112:127]
	s_waitcnt lgkmcnt(2)
	v_mfma_f32_32x32x16_bf16 v[96:111], v[208:211], v[220:223], v[96:111]
	s_waitcnt lgkmcnt(1)
	v_mfma_f32_32x32x16_bf16 v[48:63], v[208:211], v[224:227], v[48:63]
	s_waitcnt lgkmcnt(0)
	v_mfma_f32_32x32x16_bf16 v[32:47], v[208:211], v[228:231], v[32:47]
	v_mfma_f32_32x32x16_bf16 v[80:95], v[212:215], v[216:219], v[80:95]
	v_mfma_f32_32x32x16_bf16 v[64:79], v[212:215], v[220:223], v[64:79]
	v_mfma_f32_32x32x16_bf16 v[16:31], v[212:215], v[224:227], v[16:31]
	v_mfma_f32_32x32x16_bf16 v[0:15], v[212:215], v[228:231], v[0:15]
	s_and_b64 vcc, exec, s[38:39]
	s_cbranch_vccnz .LBB0_127
	s_mov_b64 s[24:25], 0x1c40080
	v_lshl_add_u64 v[148:149], v[146:147], 0, s[24:25]
	s_mov_b64 s[24:25], 0x1c60080
	v_add_u32_e32 v207, 0xc000, v206
	v_lshl_add_u64 v[146:147], v[146:147], 0, s[24:25]
	v_readfirstlane_b32 s24, v207
	s_mov_b32 m0, s24
	s_movk_i32 s25, 0x1000
	global_load_lds_dwordx4 v[148:149], off
	v_add_u32_e32 v148, 0xe000, v206
	s_nop 0
	v_readfirstlane_b32 s24, v148
	s_mov_b32 m0, s24
	s_nop 0
	global_load_lds_dwordx4 v[146:147], off
	s_branch .LBB0_127
.LBB0_134:
	s_setprio 0
	s_andn2_b64 vcc, exec, s[46:47]
	s_cbranch_vccnz .LBB0_136
	s_lshl_b32 s20, s1, 8
	s_ashr_i32 s21, s20, 31
	s_lshl_b64 s[20:21], s[20:21], 11
	v_lshl_add_u64 v[142:143], v[128:129], 0, s[20:21]
	v_readfirstlane_b32 s20, v150
	s_mov_b32 m0, s20
	s_mov_b64 s[38:39], 0x20000
	v_readfirstlane_b32 s20, v205
	s_lshl_b32 s24, s0, 8
	global_load_lds_dwordx4 v[142:143], off
	v_lshl_add_u64 v[144:145], v[142:143], 0, s[38:39]
	s_mov_b32 m0, s20
	s_mov_b64 s[46:47], 0x40000
	v_readfirstlane_b32 s20, v204
	s_ashr_i32 s25, s24, 31
	global_load_lds_dwordx4 v[144:145], off
	v_lshl_add_u64 v[144:145], v[142:143], 0, s[46:47]
	s_mov_b32 m0, s20
	s_mov_b64 s[48:49], 0x60000
	v_readfirstlane_b32 s20, v203
	s_lshl_b64 s[24:25], s[24:25], 11
	global_load_lds_dwordx4 v[144:145], off
	v_lshl_add_u64 v[142:143], v[142:143], 0, s[48:49]
	s_mov_b32 m0, s20
	v_readfirstlane_b32 s20, v202
	global_load_lds_dwordx4 v[142:143], off
	v_lshl_add_u64 v[142:143], v[130:131], 0, s[24:25]
	s_mov_b32 m0, s20
	v_readfirstlane_b32 s20, v201
	global_load_lds_dwordx4 v[142:143], off
	v_lshl_add_u64 v[144:145], v[142:143], 0, s[38:39]
	s_mov_b32 m0, s20
	v_readfirstlane_b32 s20, v200
	global_load_lds_dwordx4 v[144:145], off
	v_lshl_add_u64 v[144:145], v[142:143], 0, s[46:47]
	s_mov_b32 m0, s20
	v_readfirstlane_b32 s20, v199
	global_load_lds_dwordx4 v[144:145], off
	v_lshl_add_u64 v[142:143], v[142:143], 0, s[48:49]
	s_mov_b32 m0, s20
	s_movk_i32 s25, 0x1000
	global_load_lds_dwordx4 v[142:143], off

.LBB0_174:
	s_waitcnt vmcnt(0)
	v_mov_b32_e32 v0, 0
	v_lshl_add_u64 v[150:151], v[138:139], 0, s[52:53]
	v_lshl_add_u64 v[152:153], v[138:139], 0, s[50:51]
	s_mov_b32 s0, 0
	s_mov_b64 s[54:55], 0
	v_mov_b32_e32 v1, v0
	v_mov_b32_e32 v2, v0
	v_mov_b32_e32 v3, v0
	v_mov_b32_e32 v4, v0
	v_mov_b32_e32 v5, v0
	v_mov_b32_e32 v6, v0
	v_mov_b32_e32 v7, v0
	v_mov_b32_e32 v8, v0
	v_mov_b32_e32 v9, v0
	v_mov_b32_e32 v10, v0
	v_mov_b32_e32 v11, v0
	v_mov_b32_e32 v12, v0
	v_mov_b32_e32 v13, v0
	v_mov_b32_e32 v14, v0
	v_mov_b32_e32 v15, v0
	v_mov_b32_e32 v16, v0
	v_mov_b32_e32 v17, v0
	v_mov_b32_e32 v18, v0
	v_mov_b32_e32 v19, v0
	v_mov_b32_e32 v20, v0
	v_mov_b32_e32 v21, v0
	v_mov_b32_e32 v22, v0
	v_mov_b32_e32 v23, v0
	v_mov_b32_e32 v24, v0
	v_mov_b32_e32 v25, v0
	v_mov_b32_e32 v26, v0
	v_mov_b32_e32 v27, v0
	v_mov_b32_e32 v28, v0
	v_mov_b32_e32 v29, v0
	v_mov_b32_e32 v30, v0
	v_mov_b32_e32 v31, v0
	v_mov_b32_e32 v64, v0
	v_mov_b32_e32 v65, v0
	v_mov_b32_e32 v66, v0
	v_mov_b32_e32 v67, v0
	v_mov_b32_e32 v68, v0
	v_mov_b32_e32 v69, v0
	v_mov_b32_e32 v70, v0
	v_mov_b32_e32 v71, v0
	v_mov_b32_e32 v72, v0
	v_mov_b32_e32 v73, v0
	v_mov_b32_e32 v74, v0
	v_mov_b32_e32 v75, v0
	v_mov_b32_e32 v76, v0
	v_mov_b32_e32 v77, v0
	v_mov_b32_e32 v78, v0
	v_mov_b32_e32 v79, v0
	v_mov_b32_e32 v80, v0
	v_mov_b32_e32 v81, v0
	v_mov_b32_e32 v82, v0
	v_mov_b32_e32 v83, v0
	v_mov_b32_e32 v84, v0
	v_mov_b32_e32 v85, v0
	v_mov_b32_e32 v86, v0
	v_mov_b32_e32 v87, v0
	v_mov_b32_e32 v88, v0
	v_mov_b32_e32 v89, v0
	v_mov_b32_e32 v90, v0
	v_mov_b32_e32 v91, v0
	v_mov_b32_e32 v92, v0
	v_mov_b32_e32 v93, v0
	v_mov_b32_e32 v94, v0
	v_mov_b32_e32 v95, v0
	v_mov_b32_e32 v32, v0
	v_mov_b32_e32 v33, v0
	v_mov_b32_e32 v34, v0
	v_mov_b32_e32 v35, v0
	v_mov_b32_e32 v36, v0
	v_mov_b32_e32 v37, v0
	v_mov_b32_e32 v38, v0
	v_mov_b32_e32 v39, v0
	v_mov_b32_e32 v40, v0
	v_mov_b32_e32 v41, v0
	v_mov_b32_e32 v42, v0
	v_mov_b32_e32 v43, v0
	v_mov_b32_e32 v44, v0
	v_mov_b32_e32 v45, v0
	v_mov_b32_e32 v46, v0
	v_mov_b32_e32 v47, v0
	v_mov_b32_e32 v48, v0
	v_mov_b32_e32 v49, v0
	v_mov_b32_e32 v50, v0
	v_mov_b32_e32 v51, v0
	v_mov_b32_e32 v52, v0
	v_mov_b32_e32 v53, v0
	v_mov_b32_e32 v54, v0
	v_mov_b32_e32 v55, v0
	v_mov_b32_e32 v56, v0
	v_mov_b32_e32 v57, v0
	v_mov_b32_e32 v58, v0
	v_mov_b32_e32 v59, v0
	v_mov_b32_e32 v60, v0
	v_mov_b32_e32 v61, v0
	v_mov_b32_e32 v62, v0
	v_mov_b32_e32 v63, v0
	v_mov_b32_e32 v96, v0
	v_mov_b32_e32 v97, v0
	v_mov_b32_e32 v98, v0
	v_mov_b32_e32 v99, v0
	v_mov_b32_e32 v100, v0
	v_mov_b32_e32 v101, v0
	v_mov_b32_e32 v102, v0
	v_mov_b32_e32 v103, v0
	v_mov_b32_e32 v104, v0
	v_mov_b32_e32 v105, v0
	v_mov_b32_e32 v106, v0
	v_mov_b32_e32 v107, v0
	v_mov_b32_e32 v108, v0
	v_mov_b32_e32 v109, v0
	v_mov_b32_e32 v110, v0
	v_mov_b32_e32 v111, v0
	v_mov_b32_e32 v112, v0
	v_mov_b32_e32 v113, v0
	v_mov_b32_e32 v114, v0
	v_mov_b32_e32 v115, v0
	v_mov_b32_e32 v116, v0
	v_mov_b32_e32 v117, v0
	v_mov_b32_e32 v118, v0
	v_mov_b32_e32 v119, v0
	v_mov_b32_e32 v120, v0
	v_mov_b32_e32 v121, v0
	v_mov_b32_e32 v122, v0
	v_mov_b32_e32 v123, v0
	v_mov_b32_e32 v124, v0
	v_mov_b32_e32 v125, v0
	v_mov_b32_e32 v126, v0
	v_mov_b32_e32 v127, v0
	s_waitcnt vmcnt(0) lgkmcnt(0)
	v_readfirstlane_b32 vcc_lo, v135
	s_bitcmp1_b32 vcc_lo, 8
	s_cbranch_scc0 .Lprio_skip1
	s_setprio 1

.LBB0_175:
	v_add_u32_e32 v148, s1, v201
	v_add3_u32 v149, v148, v160, v161
	v_add3_u32 v148, v148, v198, v161
	ds_read_b128 v[144:147], v149 offset:32768
	ds_read_b128 v[154:157], v149 offset:36864
	ds_read_b128 v[214:217], v148
	ds_read_b128 v[218:221], v148 offset:4096
	ds_read_b128 v[222:225], v148 offset:8192
	ds_read_b128 v[226:229], v148 offset:12288
	s_waitcnt lgkmcnt(3)
	v_mfma_f32_32x32x16_bf16 v[112:127], v[144:147], v[214:217], v[112:127]
	s_waitcnt lgkmcnt(2)
	v_mfma_f32_32x32x16_bf16 v[96:111], v[144:147], v[218:221], v[96:111]
	s_waitcnt lgkmcnt(1)
	v_mfma_f32_32x32x16_bf16 v[48:63], v[144:147], v[222:225], v[48:63]
	s_waitcnt lgkmcnt(0)
	v_mfma_f32_32x32x16_bf16 v[32:47], v[144:147], v[226:229], v[32:47]
	v_mfma_f32_32x32x16_bf16 v[80:95], v[154:157], v[214:217], v[80:95]
	v_mfma_f32_32x32x16_bf16 v[64:79], v[154:157], v[218:221], v[64:79]
	v_mfma_f32_32x32x16_bf16 v[16:31], v[154:157], v[222:225], v[16:31]
	v_mfma_f32_32x32x16_bf16 v[0:15], v[154:157], v[226:229], v[0:15]
	s_waitcnt vmcnt(0)
	s_add_u32 s54, s54, 0x80
	s_addc_u32 s55, s55, 0
	s_cmpk_eq_i32 s54, 0x800
	s_waitcnt vmcnt(0)
	s_barrier
	s_cbranch_scc1 .LBB0_182
.LBB0_176:
	s_cmpk_lg_i32 s54, 0x780
	s_cselect_b64 s[56:57], -1, 0
	s_and_b32 s1, s0, 0x10000
	s_add_i32 s1, s1, 0
	v_add_u32_e32 v144, s1, v159
	v_add3_u32 v145, v144, v160, v161
	v_add3_u32 v144, v144, v198, v161
	ds_read_b128 v[154:157], v145 offset:32768
	ds_read_b128 v[214:217], v145 offset:36864
	ds_read_b128 v[218:221], v144
	ds_read_b128 v[222:225], v144 offset:4096
	ds_read_b128 v[226:229], v144 offset:8192
	ds_read_b128 v[230:233], v144 offset:12288
	s_add_i32 s0, s0, 0x10000
	s_and_b32 s20, s0, 0x10000
	v_lshl_add_u64 v[146:147], v[152:153], 0, s[54:55]
	s_cmpk_eq_i32 s54, 0x780
	s_waitcnt lgkmcnt(3)
	v_mfma_f32_32x32x16_bf16 v[112:127], v[154:157], v[218:221], v[112:127]
	s_waitcnt lgkmcnt(2)
	v_mfma_f32_32x32x16_bf16 v[96:111], v[154:157], v[222:225], v[96:111]
	s_waitcnt lgkmcnt(1)
	v_mfma_f32_32x32x16_bf16 v[48:63], v[154:157], v[226:229], v[48:63]
	s_waitcnt lgkmcnt(0)
	v_mfma_f32_32x32x16_bf16 v[32:47], v[154:157], v[230:233], v[32:47]
	v_mfma_f32_32x32x16_bf16 v[80:95], v[214:217], v[218:221], v[80:95]
	v_mfma_f32_32x32x16_bf16 v[64:79], v[214:217], v[222:225], v[64:79]
	v_mfma_f32_32x32x16_bf16 v[16:31], v[214:217], v[226:229], v[16:31]
	v_mfma_f32_32x32x16_bf16 v[0:15], v[214:217], v[230:233], v[0:15]
	v_add_u32_e32 v148, s20, v158
	s_cbranch_scc1 .LBB0_178
	s_mov_b64 s[20:21], 0x2dfac080
	v_lshl_add_u64 v[144:145], v[146:147], 0, s[20:21]
	s_mov_b64 s[20:21], 0x2df8c080
	v_lshl_add_u64 v[154:155], v[146:147], 0, s[20:21]
	s_mov_b64 s[20:21], 0x2df6c080
	v_lshl_add_u64 v[156:157], v[146:147], 0, s[20:21]
	v_readfirstlane_b32 s20, v148
	v_add_u32_e32 v149, 0x2000, v148
	s_mov_b32 m0, s20
	v_readfirstlane_b32 s20, v149
	v_add_u32_e32 v149, 0x4000, v148
	global_load_lds_dwordx4 v[156:157], off
	s_mov_b32 m0, s20
	v_readfirstlane_b32 s20, v149
	global_load_lds_dwordx4 v[154:155], off
	s_mov_b32 m0, s20
	s_nop 0
	global_load_lds_dwordx4 v[144:145], off
.LBB0_178:
	v_lshl_add_u64 v[144:145], v[150:151], 0, s[54:55]
	v_add_u32_e32 v149, s1, v199
	v_add3_u32 v214, v149, v160, v161
	v_add3_u32 v149, v149, v198, v161
	ds_read_b128 v[154:157], v214 offset:32768
	ds_read_b128 v[214:217], v214 offset:36864
	ds_read_b128 v[218:221], v149
	ds_read_b128 v[222:225], v149 offset:4096
	ds_read_b128 v[226:229], v149 offset:8192
	ds_read_b128 v[230:233], v149 offset:12288
	s_waitcnt lgkmcnt(3)
	v_mfma_f32_32x32x16_bf16 v[112:127], v[154:157], v[218:221], v[112:127]
	s_waitcnt lgkmcnt(2)
	v_mfma_f32_32x32x16_bf16 v[96:111], v[154:157], v[222:225], v[96:111]
	s_waitcnt lgkmcnt(1)
	v_mfma_f32_32x32x16_bf16 v[48:63], v[154:157], v[226:229], v[48:63]
	s_waitcnt lgkmcnt(0)
	v_mfma_f32_32x32x16_bf16 v[32:47], v[154:157], v[230:233], v[32:47]
	v_mfma_f32_32x32x16_bf16 v[80:95], v[214:217], v[218:221], v[80:95]
	v_mfma_f32_32x32x16_bf16 v[64:79], v[214:217], v[222:225], v[64:79]
	v_mfma_f32_32x32x16_bf16 v[16:31], v[214:217], v[226:229], v[16:31]
	v_mfma_f32_32x32x16_bf16 v[0:15], v[214:217], v[230:233], v[0:15]
	v_cndmask_b32_e64 v149, 0, 1, s[56:57]
	v_cmp_ne_u32_e64 s[38:39], 1, v149
	s_andn2_b64 vcc, exec, s[56:57]
	s_cbranch_vccnz .LBB0_180
	s_mov_b64 s[20:21], 0x2dfcc080
	v_lshl_add_u64 v[146:147], v[146:147], 0, s[20:21]
	s_mov_b64 s[20:21], 0x1600080
	v_lshl_add_u64 v[154:155], v[144:145], 0, s[20:21]
	s_mov_b64 s[20:21], 0x1620080
	v_add_u32_e32 v149, 0x6000, v148
	v_lshl_add_u64 v[156:157], v[144:145], 0, s[20:21]
	v_readfirstlane_b32 s20, v149
	s_mov_b32 m0, s20
	s_nop 0
	global_load_lds_dwordx4 v[146:147], off
	v_add_u32_e32 v146, 0x8000, v148
	s_nop 0
	v_readfirstlane_b32 s20, v146
	v_add_u32_e32 v146, 0xa000, v148
	s_mov_b32 m0, s20
	v_readfirstlane_b32 s20, v146
	global_load_lds_dwordx4 v[154:155], off
	s_mov_b32 m0, s20
	s_nop 0
	global_load_lds_dwordx4 v[156:157], off
.LBB0_180:
	v_add_u32_e32 v146, s1, v200
	v_add3_u32 v147, v146, v160, v161
	v_add3_u32 v146, v146, v198, v161
	ds_read_b128 v[154:157], v147 offset:32768
	ds_read_b128 v[214:217], v147 offset:36864
	ds_read_b128 v[218:221], v146
	ds_read_b128 v[222:225], v146 offset:4096
	ds_read_b128 v[226:229], v146 offset:8192
	ds_read_b128 v[230:233], v146 offset:12288
	s_waitcnt lgkmcnt(3)
	v_mfma_f32_32x32x16_bf16 v[112:127], v[154:157], v[218:221], v[112:127]
	s_waitcnt lgkmcnt(2)
	v_mfma_f32_32x32x16_bf16 v[96:111], v[154:157], v[222:225], v[96:111]
	s_waitcnt lgkmcnt(1)
	v_mfma_f32_32x32x16_bf16 v[48:63], v[154:157], v[226:229], v[48:63]
	s_waitcnt lgkmcnt(0)
	v_mfma_f32_32x32x16_bf16 v[32:47], v[154:157], v[230:233], v[32:47]
	v_mfma_f32_32x32x16_bf16 v[80:95], v[214:217], v[218:221], v[80:95]
	v_mfma_f32_32x32x16_bf16 v[64:79], v[214:217], v[222:225], v[64:79]
	v_mfma_f32_32x32x16_bf16 v[16:31], v[214:217], v[226:229], v[16:31]
	v_mfma_f32_32x32x16_bf16 v[0:15], v[214:217], v[230:233], v[0:15]
	s_and_b64 vcc, exec, s[38:39]
	s_cbranch_vccnz .LBB0_175
	s_mov_b64 s[20:21], 0x1640080
	v_lshl_add_u64 v[146:147], v[144:145], 0, s[20:21]
	s_mov_b64 s[20:21], 0x1660080
	v_add_u32_e32 v149, 0xc000, v148
	v_lshl_add_u64 v[144:145], v[144:145], 0, s[20:21]
	v_readfirstlane_b32 s20, v149
	s_mov_b32 m0, s20
	s_nop 0
	global_load_lds_dwordx4 v[146:147], off
	v_add_u32_e32 v146, 0xe000, v148
	s_nop 0
	v_readfirstlane_b32 s20, v146
	s_mov_b32 m0, s20
	s_nop 0
	global_load_lds_dwordx4 v[144:145], off
	s_branch .LBB0_175
.LBB0_182:
	s_setprio 0
	s_add_u32 s0, s60, s50
	s_addc_u32 s1, s61, s51
	v_lshl_add_u64 v[144:145], s[0:1], 0, v[132:133]
	v_readfirstlane_b32 s0, v158
	s_mov_b32 m0, s0
	s_mov_b64 s[38:39], 0x20000
	v_readfirstlane_b32 s0, v213
	s_add_u32 s20, s62, s52
	global_load_lds_dwordx4 v[144:145], off
	v_lshl_add_u64 v[146:147], v[144:145], 0, s[38:39]
	s_mov_b32 m0, s0
	s_mov_b64 s[50:51], 0x40000
	v_readfirstlane_b32 s0, v212
	s_addc_u32 s21, s63, s53
	global_load_lds_dwordx4 v[146:147], off
	v_lshl_add_u64 v[146:147], v[144:145], 0, s[50:51]
	s_mov_b32 m0, s0
	s_mov_b64 s[52:53], 0x60000
	v_readfirstlane_b32 s0, v211
	global_load_lds_dwordx4 v[146:147], off
	v_lshl_add_u64 v[144:145], v[144:145], 0, s[52:53]
	s_mov_b32 m0, s0
	v_readfirstlane_b32 s0, v210
	global_load_lds_dwordx4 v[144:145], off
	v_lshl_add_u64 v[144:145], s[20:21], 0, v[132:133]
	s_mov_b32 m0, s0
	v_readfirstlane_b32 s0, v209
	global_load_lds_dwordx4 v[144:145], off
	v_lshl_add_u64 v[146:147], v[144:145], 0, s[38:39]
	s_mov_b32 m0, s0
	v_readfirstlane_b32 s0, v208
	global_load_lds_dwordx4 v[146:147], off
	v_lshl_add_u64 v[146:147], v[144:145], 0, s[50:51]
	s_mov_b32 m0, s0
	v_readfirstlane_b32 s0, v207
	global_load_lds_dwordx4 v[146:147], off
	v_lshl_add_u64 v[144:145], v[144:145], 0, s[52:53]
	s_mov_b32 m0, s0
	v_cvt_pk_bf16_f32 v112, v112, v113
	global_load_lds_dwordx4 v[144:145], off
	v_add_u32_e32 v144, s48, v203
	v_ashrrev_i32_e32 v145, 31, v144
	v_cvt_pk_bf16_f32 v113, v114, v115
	ds_write_b64 v205, v[112:113]
	v_cvt_pk_bf16_f32 v112, v116, v117
	v_cvt_pk_bf16_f32 v113, v118, v119
	ds_write_b64 v205, v[112:113] offset:16
	v_cvt_pk_bf16_f32 v112, v120, v121
	v_cvt_pk_bf16_f32 v113, v122, v123
	ds_write_b64 v205, v[112:113] offset:32
	v_cvt_pk_bf16_f32 v112, v124, v125
	v_cvt_pk_bf16_f32 v113, v126, v127
	ds_write_b64 v205, v[112:113] offset:48
	v_cvt_pk_bf16_f32 v96, v96, v97
	v_cvt_pk_bf16_f32 v97, v98, v99
	ds_write_b64 v206, v[96:97]
	v_cvt_pk_bf16_f32 v96, v100, v101
	v_cvt_pk_bf16_f32 v97, v102, v103
	ds_write_b64 v206, v[96:97] offset:16
	v_cvt_pk_bf16_f32 v96, v104, v105
	v_cvt_pk_bf16_f32 v97, v106, v107
	ds_write_b64 v206, v[96:97] offset:32
	v_cvt_pk_bf16_f32 v96, v108, v109
	v_cvt_pk_bf16_f32 v97, v110, v111
	ds_write_b64 v206, v[96:97] offset:48
	v_cvt_pk_bf16_f32 v80, v80, v81
	v_cvt_pk_bf16_f32 v81, v82, v83
	ds_write_b64 v205, v[80:81] offset:64
	v_cvt_pk_bf16_f32 v80, v84, v85
	v_cvt_pk_bf16_f32 v81, v86, v87
	ds_write_b64 v205, v[80:81] offset:80
	v_cvt_pk_bf16_f32 v80, v88, v89
	v_cvt_pk_bf16_f32 v81, v90, v91
	ds_write_b64 v205, v[80:81] offset:96
	v_cvt_pk_bf16_f32 v80, v92, v93
	v_cvt_pk_bf16_f32 v81, v94, v95
	ds_write_b64 v205, v[80:81] offset:112
	v_cvt_pk_bf16_f32 v64, v64, v65
	v_cvt_pk_bf16_f32 v65, v66, v67
	ds_write_b64 v206, v[64:65] offset:64
	v_cvt_pk_bf16_f32 v64, v68, v69
	v_cvt_pk_bf16_f32 v65, v70, v71
	ds_write_b64 v206, v[64:65] offset:80
	v_cvt_pk_bf16_f32 v64, v72, v73
	v_cvt_pk_bf16_f32 v65, v74, v75
	ds_write_b64 v206, v[64:65] offset:96
	v_cvt_pk_bf16_f32 v64, v76, v77
	v_cvt_pk_bf16_f32 v65, v78, v79
	ds_write_b64 v206, v[64:65] offset:112
	v_add_u32_e32 v64, s34, v202
	v_ashrrev_i32_e32 v65, 31, v64
	v_lshlrev_b64 v[66:67], 11, v[64:65]
	v_lshl_add_u64 v[146:147], v[140:141], 0, v[66:67]
	v_mad_i64_i32 v[148:149], s[0:1], v64, s33, v[142:143]
	v_lshlrev_b64 v[144:145], 1, v[144:145]
	s_mov_b32 s0, 0
	v_mov_b64_e32 v[64:65], v[148:149]
	v_mov_b64_e32 v[66:67], v[146:147]
	s_mov_b32 s20, 0x8ba5000
	s_mov_b32 s21, 0x31f70000
	s_mov_b32 s34, 0x8bd9000
	s_mov_b32 s35, 0x31f74000
	s_mov_b32 s38, 0x8c0d000
	s_mov_b64 s[48:49], 0x10000
	s_mov_b64 s[50:51], 0xd0000

.LBB0_185:
	s_nop 0
	v_add_u32_e32 v8, s0, v204
	v_add_u32_e32 v4, 0x10000, v8
	ds_read_b128 v[10:13], v4
	v_lshl_add_u64 v[4:5], v[0:1], 0, v[144:145]
	v_add_co_u32_e32 v6, vcc, 0x8d11000, v4
	s_mov_b32 s1, 0x31f8c000
	s_nop 0
	v_addc_co_u32_e32 v7, vcc, 0, v5, vcc
	global_load_dwordx4 v[14:17], v[6:7], off
	s_waitcnt lgkmcnt(0)
	v_lshlrev_b32_e32 v6, 16, v10
	v_and_b32_e32 v7, 0xffff0000, v10
	v_add_u32_e32 v9, 0x10480, v8
	s_addk_i32 s0, 0x1200
	v_lshl_add_u64 v[0:1], v[0:1], 0, s[50:51]
	s_cmpk_eq_i32 s0, 0x2400
	s_waitcnt vmcnt(0)
	v_lshlrev_b32_e32 v18, 16, v14
	v_and_b32_e32 v19, 0xffff0000, v14
	v_pk_mul_f32 v[6:7], v[6:7], v[18:19]
	v_lshlrev_b32_e32 v14, 16, v15
	v_cvt_pk_bf16_f32 v10, v6, v7
	v_lshlrev_b32_e32 v6, 16, v11
	v_and_b32_e32 v7, 0xffff0000, v11
	v_and_b32_e32 v15, 0xffff0000, v15
	v_pk_mul_f32 v[6:7], v[6:7], v[14:15]
	v_lshlrev_b32_e32 v14, 16, v16
	v_cvt_pk_bf16_f32 v11, v6, v7
	v_lshlrev_b32_e32 v6, 16, v12
	v_and_b32_e32 v7, 0xffff0000, v12
	v_and_b32_e32 v15, 0xffff0000, v16
	v_pk_mul_f32 v[6:7], v[6:7], v[14:15]
	v_lshlrev_b32_e32 v14, 16, v17
	v_cvt_pk_bf16_f32 v12, v6, v7
	v_lshlrev_b32_e32 v6, 16, v13
	v_and_b32_e32 v7, 0xffff0000, v13
	v_and_b32_e32 v15, 0xffff0000, v17
	v_pk_mul_f32 v[6:7], v[6:7], v[14:15]
	s_nop 0
	v_cvt_pk_bf16_f32 v13, v6, v7
	v_lshl_add_u64 v[6:7], v[2:3], 0, v[144:145]
	v_add_co_u32_e32 v14, vcc, s1, v6
	v_lshl_add_u64 v[2:3], v[2:3], 0, s[48:49]
	s_nop 0
	v_addc_co_u32_e32 v15, vcc, 0, v7, vcc
	global_store_dwordx4 v[14:15], v[10:13], off
	v_add_co_u32_e32 v14, vcc, s20, v4
	ds_read_b128 v[10:13], v9
	s_nop 0
	v_addc_co_u32_e32 v15, vcc, 0, v5, vcc
	global_load_dwordx4 v[14:17], v[14:15], off
	v_add_u32_e32 v9, 0x10900, v8
	s_waitcnt lgkmcnt(0)
	v_lshlrev_b32_e32 v18, 16, v10
	v_and_b32_e32 v19, 0xffff0000, v10
	v_add_u32_e32 v8, 0x10d80, v8
	s_waitcnt vmcnt(0)
	v_lshlrev_b32_e32 v20, 16, v14
	v_and_b32_e32 v21, 0xffff0000, v14
	v_pk_mul_f32 v[18:19], v[18:19], v[20:21]
	v_lshlrev_b32_e32 v14, 16, v15
	v_cvt_pk_bf16_f32 v10, v18, v19
	v_lshlrev_b32_e32 v18, 16, v11
	v_and_b32_e32 v19, 0xffff0000, v11
	v_and_b32_e32 v15, 0xffff0000, v15
	v_pk_mul_f32 v[14:15], v[18:19], v[14:15]
	v_lshlrev_b32_e32 v18, 16, v16
	v_cvt_pk_bf16_f32 v11, v14, v15
	v_lshlrev_b32_e32 v14, 16, v12
	v_and_b32_e32 v15, 0xffff0000, v12
	v_and_b32_e32 v19, 0xffff0000, v16
	v_pk_mul_f32 v[14:15], v[14:15], v[18:19]
	v_lshlrev_b32_e32 v16, 16, v17
	v_cvt_pk_bf16_f32 v12, v14, v15
	v_lshlrev_b32_e32 v14, 16, v13
	v_and_b32_e32 v15, 0xffff0000, v13
	v_and_b32_e32 v17, 0xffff0000, v17
	v_pk_mul_f32 v[14:15], v[14:15], v[16:17]
	s_nop 0
	v_cvt_pk_bf16_f32 v13, v14, v15
	v_add_co_u32_e32 v14, vcc, s21, v6
	s_nop 1
	v_addc_co_u32_e32 v15, vcc, 0, v7, vcc
	global_store_dwordx4 v[14:15], v[10:13], off
	v_add_co_u32_e32 v14, vcc, s34, v4
	ds_read_b128 v[10:13], v9
	s_nop 0
	v_addc_co_u32_e32 v15, vcc, 0, v5, vcc
	global_load_dwordx4 v[14:17], v[14:15], off
	s_waitcnt lgkmcnt(0)
	v_lshlrev_b32_e32 v18, 16, v10
	v_and_b32_e32 v19, 0xffff0000, v10
	s_waitcnt vmcnt(0)
	v_lshlrev_b32_e32 v20, 16, v14
	v_and_b32_e32 v21, 0xffff0000, v14
	v_pk_mul_f32 v[18:19], v[18:19], v[20:21]
	v_lshlrev_b32_e32 v14, 16, v15
	v_cvt_pk_bf16_f32 v10, v18, v19
	v_lshlrev_b32_e32 v18, 16, v11
	v_and_b32_e32 v19, 0xffff0000, v11
	v_and_b32_e32 v15, 0xffff0000, v15
	v_pk_mul_f32 v[14:15], v[18:19], v[14:15]
	v_lshlrev_b32_e32 v18, 16, v16
	v_cvt_pk_bf16_f32 v11, v14, v15
	v_lshlrev_b32_e32 v14, 16, v12
	v_and_b32_e32 v15, 0xffff0000, v12
	v_and_b32_e32 v19, 0xffff0000, v16
	v_pk_mul_f32 v[14:15], v[14:15], v[18:19]
	v_lshlrev_b32_e32 v16, 16, v17
	v_cvt_pk_bf16_f32 v12, v14, v15
	v_lshlrev_b32_e32 v14, 16, v13
	v_and_b32_e32 v15, 0xffff0000, v13
	v_and_b32_e32 v17, 0xffff0000, v17
	v_pk_mul_f32 v[14:15], v[14:15], v[16:17]
	s_nop 0
	v_cvt_pk_bf16_f32 v13, v14, v15
	v_add_co_u32_e32 v14, vcc, s35, v6
	s_nop 1
	v_addc_co_u32_e32 v15, vcc, 0, v7, vcc
	v_add_co_u32_e32 v4, vcc, s38, v4
	global_store_dwordx4 v[14:15], v[10:13], off
	s_nop 0
	v_addc_co_u32_e32 v5, vcc, 0, v5, vcc
	global_load_dwordx4 v[12:15], v[4:5], off
	ds_read_b128 v[8:11], v8
	s_waitcnt lgkmcnt(0)
	v_lshlrev_b32_e32 v4, 16, v8
	v_and_b32_e32 v5, 0xffff0000, v8
	s_waitcnt vmcnt(0)
	v_lshlrev_b32_e32 v16, 16, v12
	v_and_b32_e32 v17, 0xffff0000, v12
	v_pk_mul_f32 v[4:5], v[4:5], v[16:17]
	v_lshlrev_b32_e32 v12, 16, v13
	v_cvt_pk_bf16_f32 v8, v4, v5
	v_lshlrev_b32_e32 v4, 16, v9
	v_and_b32_e32 v5, 0xffff0000, v9
	v_and_b32_e32 v13, 0xffff0000, v13
	v_pk_mul_f32 v[4:5], v[4:5], v[12:13]
	v_lshlrev_b32_e32 v12, 16, v14
	v_cvt_pk_bf16_f32 v9, v4, v5
	v_lshlrev_b32_e32 v4, 16, v10
	v_and_b32_e32 v5, 0xffff0000, v10
	v_and_b32_e32 v13, 0xffff0000, v14
	v_pk_mul_f32 v[4:5], v[4:5], v[12:13]
	v_lshlrev_b32_e32 v12, 16, v15
	v_cvt_pk_bf16_f32 v10, v4, v5
	v_lshlrev_b32_e32 v4, 16, v11
	v_and_b32_e32 v5, 0xffff0000, v11
	v_and_b32_e32 v13, 0xffff0000, v15
	v_pk_mul_f32 v[4:5], v[4:5], v[12:13]
	s_nop 0
	v_cvt_pk_bf16_f32 v11, v4, v5
	v_add_co_u32_e32 v4, vcc, 0x31f98000, v6
	s_nop 1
	v_addc_co_u32_e32 v5, vcc, 0, v7, vcc
	global_store_dwordx4 v[4:5], v[8:11], off
	s_cbranch_scc0 .LBB0_185
	s_waitcnt vmcnt(0)
	v_mov_b32_e32 v0, 0
	s_mov_b32 s0, 0
	s_mov_b64 s[34:35], 0
	v_mov_b32_e32 v1, v0
	v_mov_b32_e32 v2, v0
	v_mov_b32_e32 v3, v0
	v_mov_b32_e32 v4, v0
	v_mov_b32_e32 v5, v0
	v_mov_b32_e32 v6, v0
	v_mov_b32_e32 v7, v0
	v_mov_b32_e32 v8, v0
	v_mov_b32_e32 v9, v0
	v_mov_b32_e32 v10, v0
	v_mov_b32_e32 v11, v0
	v_mov_b32_e32 v12, v0
	v_mov_b32_e32 v13, v0
	v_mov_b32_e32 v14, v0
	v_mov_b32_e32 v15, v0
	v_mov_b32_e32 v16, v0
	v_mov_b32_e32 v17, v0
	v_mov_b32_e32 v18, v0
	v_mov_b32_e32 v19, v0
	v_mov_b32_e32 v20, v0
	v_mov_b32_e32 v21, v0
	v_mov_b32_e32 v22, v0
	v_mov_b32_e32 v23, v0
	v_mov_b32_e32 v24, v0
	v_mov_b32_e32 v25, v0
	v_mov_b32_e32 v26, v0
	v_mov_b32_e32 v27, v0
	v_mov_b32_e32 v28, v0
	v_mov_b32_e32 v29, v0
	v_mov_b32_e32 v30, v0
	v_mov_b32_e32 v31, v0
	v_mov_b32_e32 v64, v0
	v_mov_b32_e32 v65, v0
	v_mov_b32_e32 v66, v0
	v_mov_b32_e32 v67, v0
	v_mov_b32_e32 v68, v0
	v_mov_b32_e32 v69, v0
	v_mov_b32_e32 v70, v0
	v_mov_b32_e32 v71, v0
	v_mov_b32_e32 v72, v0
	v_mov_b32_e32 v73, v0
	v_mov_b32_e32 v74, v0
	v_mov_b32_e32 v75, v0
	v_mov_b32_e32 v76, v0
	v_mov_b32_e32 v77, v0
	v_mov_b32_e32 v78, v0
	v_mov_b32_e32 v79, v0
	v_mov_b32_e32 v80, v0
	v_mov_b32_e32 v81, v0
	v_mov_b32_e32 v82, v0
	v_mov_b32_e32 v83, v0
	v_mov_b32_e32 v84, v0
	v_mov_b32_e32 v85, v0
	v_mov_b32_e32 v86, v0
	v_mov_b32_e32 v87, v0
	v_mov_b32_e32 v88, v0
	v_mov_b32_e32 v89, v0
	v_mov_b32_e32 v90, v0
	v_mov_b32_e32 v91, v0
	v_mov_b32_e32 v92, v0
	v_mov_b32_e32 v93, v0
	v_mov_b32_e32 v94, v0
	v_mov_b32_e32 v95, v0
	v_mov_b32_e32 v32, v0
	v_mov_b32_e32 v33, v0
	v_mov_b32_e32 v34, v0
	v_mov_b32_e32 v35, v0
	v_mov_b32_e32 v36, v0
	v_mov_b32_e32 v37, v0
	v_mov_b32_e32 v38, v0
	v_mov_b32_e32 v39, v0
	v_mov_b32_e32 v40, v0
	v_mov_b32_e32 v41, v0
	v_mov_b32_e32 v42, v0
	v_mov_b32_e32 v43, v0
	v_mov_b32_e32 v44, v0
	v_mov_b32_e32 v45, v0
	v_mov_b32_e32 v46, v0
	v_mov_b32_e32 v47, v0
	v_mov_b32_e32 v48, v0
	v_mov_b32_e32 v49, v0
	v_mov_b32_e32 v50, v0
	v_mov_b32_e32 v51, v0
	v_mov_b32_e32 v52, v0
	v_mov_b32_e32 v53, v0
	v_mov_b32_e32 v54, v0
	v_mov_b32_e32 v55, v0
	v_mov_b32_e32 v56, v0
	v_mov_b32_e32 v57, v0
	v_mov_b32_e32 v58, v0
	v_mov_b32_e32 v59, v0
	v_mov_b32_e32 v60, v0
	v_mov_b32_e32 v61, v0
	v_mov_b32_e32 v62, v0
	v_mov_b32_e32 v63, v0
	v_mov_b32_e32 v96, v0
	v_mov_b32_e32 v97, v0
	v_mov_b32_e32 v98, v0
	v_mov_b32_e32 v99, v0
	v_mov_b32_e32 v100, v0
	v_mov_b32_e32 v101, v0
	v_mov_b32_e32 v102, v0
	v_mov_b32_e32 v103, v0
	v_mov_b32_e32 v104, v0
	v_mov_b32_e32 v105, v0
	v_mov_b32_e32 v106, v0
	v_mov_b32_e32 v107, v0
	v_mov_b32_e32 v108, v0
	v_mov_b32_e32 v109, v0
	v_mov_b32_e32 v110, v0
	v_mov_b32_e32 v111, v0
	v_mov_b32_e32 v112, v0
	v_mov_b32_e32 v113, v0
	v_mov_b32_e32 v114, v0
	v_mov_b32_e32 v115, v0
	v_mov_b32_e32 v116, v0
	v_mov_b32_e32 v117, v0
	v_mov_b32_e32 v118, v0
	v_mov_b32_e32 v119, v0
	v_mov_b32_e32 v120, v0
	v_mov_b32_e32 v121, v0
	v_mov_b32_e32 v122, v0
	v_mov_b32_e32 v123, v0
	v_mov_b32_e32 v124, v0
	v_mov_b32_e32 v125, v0
	v_mov_b32_e32 v126, v0
	v_mov_b32_e32 v127, v0
	v_readfirstlane_b32 vcc_lo, v135
	s_bitcmp1_b32 vcc_lo, 8
	s_cbranch_scc0 .Lprio_skip2
	s_setprio 1

.LBB0_187:
	v_add_u32_e32 v218, s1, v201
	v_add3_u32 v214, v218, v160, v161
	v_add3_u32 v230, v218, v198, v161
	ds_read_b128 v[154:157], v214 offset:32768
	ds_read_b128 v[214:217], v214 offset:36864
	ds_read_b128 v[218:221], v230
	ds_read_b128 v[222:225], v230 offset:4096
	ds_read_b128 v[226:229], v230 offset:8192
	ds_read_b128 v[230:233], v230 offset:12288
	s_waitcnt lgkmcnt(3)
	v_mfma_f32_32x32x16_bf16 v[112:127], v[154:157], v[218:221], v[112:127]
	s_waitcnt lgkmcnt(2)
	v_mfma_f32_32x32x16_bf16 v[96:111], v[154:157], v[222:225], v[96:111]
	s_waitcnt lgkmcnt(1)
	v_mfma_f32_32x32x16_bf16 v[48:63], v[154:157], v[226:229], v[48:63]
	s_waitcnt lgkmcnt(0)
	v_mfma_f32_32x32x16_bf16 v[32:47], v[154:157], v[230:233], v[32:47]
	v_mfma_f32_32x32x16_bf16 v[80:95], v[214:217], v[218:221], v[80:95]
	v_mfma_f32_32x32x16_bf16 v[64:79], v[214:217], v[222:225], v[64:79]
	v_mfma_f32_32x32x16_bf16 v[16:31], v[214:217], v[226:229], v[16:31]
	v_mfma_f32_32x32x16_bf16 v[0:15], v[214:217], v[230:233], v[0:15]
	s_waitcnt vmcnt(0)
	s_add_u32 s34, s34, 0x80
	s_addc_u32 s35, s35, 0
	s_cmpk_eq_i32 s34, 0x800
	s_waitcnt vmcnt(0)
	s_barrier
	s_cbranch_scc1 .LBB0_194
.LBB0_188:
	s_cmpk_lg_i32 s34, 0x780
	s_cselect_b64 s[48:49], -1, 0
	s_and_b32 s1, s0, 0x10000
	s_add_i32 s1, s1, 0
	v_add_u32_e32 v154, s1, v159
	v_add3_u32 v155, v154, v160, v161
	v_add3_u32 v154, v154, v198, v161
	ds_read_b128 v[214:217], v155 offset:32768
	ds_read_b128 v[218:221], v155 offset:36864
	ds_read_b128 v[222:225], v154
	ds_read_b128 v[226:229], v154 offset:4096
	ds_read_b128 v[230:233], v154 offset:8192
	ds_read_b128 v[234:237], v154 offset:12288
	s_add_i32 s0, s0, 0x10000
	s_and_b32 s20, s0, 0x10000
	v_lshl_add_u64 v[156:157], v[152:153], 0, s[34:35]
	s_cmpk_eq_i32 s34, 0x780
	s_waitcnt lgkmcnt(3)
	v_mfma_f32_32x32x16_bf16 v[112:127], v[214:217], v[222:225], v[112:127]
	s_waitcnt lgkmcnt(2)
	v_mfma_f32_32x32x16_bf16 v[96:111], v[214:217], v[226:229], v[96:111]
	s_waitcnt lgkmcnt(1)
	v_mfma_f32_32x32x16_bf16 v[48:63], v[214:217], v[230:233], v[48:63]
	s_waitcnt lgkmcnt(0)
	v_mfma_f32_32x32x16_bf16 v[32:47], v[214:217], v[234:237], v[32:47]
	v_mfma_f32_32x32x16_bf16 v[80:95], v[218:221], v[222:225], v[80:95]
	v_mfma_f32_32x32x16_bf16 v[64:79], v[218:221], v[226:229], v[64:79]
	v_mfma_f32_32x32x16_bf16 v[16:31], v[218:221], v[230:233], v[16:31]
	v_mfma_f32_32x32x16_bf16 v[0:15], v[218:221], v[234:237], v[0:15]
	v_add_u32_e32 v214, s20, v158
	s_cbranch_scc1 .LBB0_190
	s_mov_b64 s[20:21], 0x2ffac080
	v_lshl_add_u64 v[154:155], v[156:157], 0, s[20:21]
	s_mov_b64 s[20:21], 0x2ff8c080
	v_lshl_add_u64 v[216:217], v[156:157], 0, s[20:21]
	s_mov_b64 s[20:21], 0x2ff6c080
	v_lshl_add_u64 v[218:219], v[156:157], 0, s[20:21]
	v_readfirstlane_b32 s20, v214
	v_add_u32_e32 v215, 0x2000, v214
	s_mov_b32 m0, s20
	v_readfirstlane_b32 s20, v215
	v_add_u32_e32 v215, 0x4000, v214
	global_load_lds_dwordx4 v[218:219], off
	s_mov_b32 m0, s20
	v_readfirstlane_b32 s20, v215
	global_load_lds_dwordx4 v[216:217], off
	s_mov_b32 m0, s20
	s_nop 0
	global_load_lds_dwordx4 v[154:155], off
.LBB0_190:
	v_lshl_add_u64 v[154:155], v[150:151], 0, s[34:35]
	v_add_u32_e32 v215, s1, v199
	v_add3_u32 v220, v215, v160, v161
	v_add3_u32 v215, v215, v198, v161
	ds_read_b128 v[216:219], v220 offset:32768
	ds_read_b128 v[220:223], v220 offset:36864
	ds_read_b128 v[224:227], v215
	ds_read_b128 v[228:231], v215 offset:4096
	ds_read_b128 v[232:235], v215 offset:8192
	ds_read_b128 v[236:239], v215 offset:12288
	s_waitcnt lgkmcnt(3)
	v_mfma_f32_32x32x16_bf16 v[112:127], v[216:219], v[224:227], v[112:127]
	s_waitcnt lgkmcnt(2)
	v_mfma_f32_32x32x16_bf16 v[96:111], v[216:219], v[228:231], v[96:111]
	s_waitcnt lgkmcnt(1)
	v_mfma_f32_32x32x16_bf16 v[48:63], v[216:219], v[232:235], v[48:63]
	s_waitcnt lgkmcnt(0)
	v_mfma_f32_32x32x16_bf16 v[32:47], v[216:219], v[236:239], v[32:47]
	v_mfma_f32_32x32x16_bf16 v[80:95], v[220:223], v[224:227], v[80:95]
	v_mfma_f32_32x32x16_bf16 v[64:79], v[220:223], v[228:231], v[64:79]
	v_mfma_f32_32x32x16_bf16 v[16:31], v[220:223], v[232:235], v[16:31]
	v_mfma_f32_32x32x16_bf16 v[0:15], v[220:223], v[236:239], v[0:15]
	v_cndmask_b32_e64 v215, 0, 1, s[48:49]
	v_cmp_ne_u32_e64 s[38:39], 1, v215
	s_andn2_b64 vcc, exec, s[48:49]
	s_cbranch_vccnz .LBB0_192
	s_mov_b64 s[20:21], 0x2ffcc080
	v_lshl_add_u64 v[156:157], v[156:157], 0, s[20:21]
	s_mov_b64 s[20:21], 0x1800080
	v_lshl_add_u64 v[216:217], v[154:155], 0, s[20:21]
	s_mov_b64 s[20:21], 0x1820080
	v_add_u32_e32 v215, 0x6000, v214
	v_lshl_add_u64 v[218:219], v[154:155], 0, s[20:21]
	v_readfirstlane_b32 s20, v215
	s_mov_b32 m0, s20
	s_nop 0
	global_load_lds_dwordx4 v[156:157], off
	v_add_u32_e32 v156, 0x8000, v214
	s_nop 0
	v_readfirstlane_b32 s20, v156
	v_add_u32_e32 v156, 0xa000, v214
	s_mov_b32 m0, s20
	v_readfirstlane_b32 s20, v156
	global_load_lds_dwordx4 v[216:217], off
	s_mov_b32 m0, s20
	s_nop 0
	global_load_lds_dwordx4 v[218:219], off
.LBB0_192:
	v_add_u32_e32 v156, s1, v200
	v_add3_u32 v157, v156, v160, v161
	v_add3_u32 v156, v156, v198, v161
	ds_read_b128 v[216:219], v157 offset:32768
	ds_read_b128 v[220:223], v157 offset:36864
	ds_read_b128 v[224:227], v156
	ds_read_b128 v[228:231], v156 offset:4096
	ds_read_b128 v[232:235], v156 offset:8192
	ds_read_b128 v[236:239], v156 offset:12288
	s_waitcnt lgkmcnt(3)
	v_mfma_f32_32x32x16_bf16 v[112:127], v[216:219], v[224:227], v[112:127]
	s_waitcnt lgkmcnt(2)
	v_mfma_f32_32x32x16_bf16 v[96:111], v[216:219], v[228:231], v[96:111]
	s_waitcnt lgkmcnt(1)
	v_mfma_f32_32x32x16_bf16 v[48:63], v[216:219], v[232:235], v[48:63]
	s_waitcnt lgkmcnt(0)
	v_mfma_f32_32x32x16_bf16 v[32:47], v[216:219], v[236:239], v[32:47]
	v_mfma_f32_32x32x16_bf16 v[80:95], v[220:223], v[224:227], v[80:95]
	v_mfma_f32_32x32x16_bf16 v[64:79], v[220:223], v[228:231], v[64:79]
	v_mfma_f32_32x32x16_bf16 v[16:31], v[220:223], v[232:235], v[16:31]
	v_mfma_f32_32x32x16_bf16 v[0:15], v[220:223], v[236:239], v[0:15]
	s_and_b64 vcc, exec, s[38:39]
	s_cbranch_vccnz .LBB0_187
	s_mov_b64 s[20:21], 0x1840080
	v_lshl_add_u64 v[156:157], v[154:155], 0, s[20:21]
	s_mov_b64 s[20:21], 0x1860080
	v_add_u32_e32 v215, 0xc000, v214
	v_lshl_add_u64 v[154:155], v[154:155], 0, s[20:21]
	v_readfirstlane_b32 s20, v215
	s_mov_b32 m0, s20
	s_nop 0
	global_load_lds_dwordx4 v[156:157], off
	v_add_u32_e32 v156, 0xe000, v214
	s_nop 0
	v_readfirstlane_b32 s20, v156
	s_mov_b32 m0, s20
	s_nop 0
	global_load_lds_dwordx4 v[154:155], off
	s_branch .LBB0_187
.LBB0_194:
	s_setprio 0
	s_andn2_b64 vcc, exec, s[46:47]
	s_cbranch_vccnz .LBB0_196
	s_lshl_b32 s0, s65, 8
	s_ashr_i32 s1, s0, 31
	s_lshl_b64 s[0:1], s[0:1], 11
	v_lshl_add_u64 v[150:151], v[128:129], 0, s[0:1]
	v_readfirstlane_b32 s0, v158
	s_mov_b32 m0, s0
	s_mov_b64 s[34:35], 0x20000
	v_readfirstlane_b32 s0, v213
	s_lshl_b32 s20, s64, 8
	global_load_lds_dwordx4 v[150:151], off
	v_lshl_add_u64 v[152:153], v[150:151], 0, s[34:35]
	s_mov_b32 m0, s0
	s_mov_b64 s[38:39], 0x40000
	v_readfirstlane_b32 s0, v212
	s_ashr_i32 s21, s20, 31
	global_load_lds_dwordx4 v[152:153], off
	v_lshl_add_u64 v[152:153], v[150:151], 0, s[38:39]
	s_mov_b32 m0, s0
	s_mov_b64 s[46:47], 0x60000
	v_readfirstlane_b32 s0, v211
	s_lshl_b64 s[20:21], s[20:21], 11
	global_load_lds_dwordx4 v[152:153], off
	v_lshl_add_u64 v[150:151], v[150:151], 0, s[46:47]
	s_mov_b32 m0, s0
	v_readfirstlane_b32 s0, v210
	global_load_lds_dwordx4 v[150:151], off
	v_lshl_add_u64 v[150:151], v[130:131], 0, s[20:21]
	s_mov_b32 m0, s0
	v_readfirstlane_b32 s0, v209
	global_load_lds_dwordx4 v[150:151], off
	v_lshl_add_u64 v[152:153], v[150:151], 0, s[34:35]
	s_mov_b32 m0, s0
	v_readfirstlane_b32 s0, v208
	global_load_lds_dwordx4 v[152:153], off
	v_lshl_add_u64 v[152:153], v[150:151], 0, s[38:39]
	s_mov_b32 m0, s0
	v_readfirstlane_b32 s0, v207
	global_load_lds_dwordx4 v[152:153], off
	v_lshl_add_u64 v[150:151], v[150:151], 0, s[46:47]
	s_mov_b32 m0, s0
	s_nop 0
	global_load_lds_dwordx4 v[150:151], off

.LBB0_330:
	s_waitcnt vmcnt(0)
	v_mov_b32_e32 v0, 0
	v_lshl_add_u64 v[146:147], v[140:141], 0, s[50:51]
	v_lshl_add_u64 v[148:149], v[140:141], 0, s[38:39]
	s_mov_b32 s0, 0
	s_mov_b64 s[50:51], 0
	v_mov_b32_e32 v1, v0
	v_mov_b32_e32 v2, v0
	v_mov_b32_e32 v3, v0
	v_mov_b32_e32 v4, v0
	v_mov_b32_e32 v5, v0
	v_mov_b32_e32 v6, v0
	v_mov_b32_e32 v7, v0
	v_mov_b32_e32 v8, v0
	v_mov_b32_e32 v9, v0
	v_mov_b32_e32 v10, v0
	v_mov_b32_e32 v11, v0
	v_mov_b32_e32 v12, v0
	v_mov_b32_e32 v13, v0
	v_mov_b32_e32 v14, v0
	v_mov_b32_e32 v15, v0
	v_mov_b32_e32 v16, v0
	v_mov_b32_e32 v17, v0
	v_mov_b32_e32 v18, v0
	v_mov_b32_e32 v19, v0
	v_mov_b32_e32 v20, v0
	v_mov_b32_e32 v21, v0
	v_mov_b32_e32 v22, v0
	v_mov_b32_e32 v23, v0
	v_mov_b32_e32 v24, v0
	v_mov_b32_e32 v25, v0
	v_mov_b32_e32 v26, v0
	v_mov_b32_e32 v27, v0
	v_mov_b32_e32 v28, v0
	v_mov_b32_e32 v29, v0
	v_mov_b32_e32 v30, v0
	v_mov_b32_e32 v31, v0
	v_mov_b32_e32 v64, v0
	v_mov_b32_e32 v65, v0
	v_mov_b32_e32 v66, v0
	v_mov_b32_e32 v67, v0
	v_mov_b32_e32 v68, v0
	v_mov_b32_e32 v69, v0
	v_mov_b32_e32 v70, v0
	v_mov_b32_e32 v71, v0
	v_mov_b32_e32 v72, v0
	v_mov_b32_e32 v73, v0
	v_mov_b32_e32 v74, v0
	v_mov_b32_e32 v75, v0
	v_mov_b32_e32 v76, v0
	v_mov_b32_e32 v77, v0
	v_mov_b32_e32 v78, v0
	v_mov_b32_e32 v79, v0
	v_mov_b32_e32 v80, v0
	v_mov_b32_e32 v81, v0
	v_mov_b32_e32 v82, v0
	v_mov_b32_e32 v83, v0
	v_mov_b32_e32 v84, v0
	v_mov_b32_e32 v85, v0
	v_mov_b32_e32 v86, v0
	v_mov_b32_e32 v87, v0
	v_mov_b32_e32 v88, v0
	v_mov_b32_e32 v89, v0
	v_mov_b32_e32 v90, v0
	v_mov_b32_e32 v91, v0
	v_mov_b32_e32 v92, v0
	v_mov_b32_e32 v93, v0
	v_mov_b32_e32 v94, v0
	v_mov_b32_e32 v95, v0
	v_mov_b32_e32 v32, v0
	v_mov_b32_e32 v33, v0
	v_mov_b32_e32 v34, v0
	v_mov_b32_e32 v35, v0
	v_mov_b32_e32 v36, v0
	v_mov_b32_e32 v37, v0
	v_mov_b32_e32 v38, v0
	v_mov_b32_e32 v39, v0
	v_mov_b32_e32 v40, v0
	v_mov_b32_e32 v41, v0
	v_mov_b32_e32 v42, v0
	v_mov_b32_e32 v43, v0
	v_mov_b32_e32 v44, v0
	v_mov_b32_e32 v45, v0
	v_mov_b32_e32 v46, v0
	v_mov_b32_e32 v47, v0
	v_mov_b32_e32 v48, v0
	v_mov_b32_e32 v49, v0
	v_mov_b32_e32 v50, v0
	v_mov_b32_e32 v51, v0
	v_mov_b32_e32 v52, v0
	v_mov_b32_e32 v53, v0
	v_mov_b32_e32 v54, v0
	v_mov_b32_e32 v55, v0
	v_mov_b32_e32 v56, v0
	v_mov_b32_e32 v57, v0
	v_mov_b32_e32 v58, v0
	v_mov_b32_e32 v59, v0
	v_mov_b32_e32 v60, v0
	v_mov_b32_e32 v61, v0
	v_mov_b32_e32 v62, v0
	v_mov_b32_e32 v63, v0
	v_mov_b32_e32 v96, v0
	v_mov_b32_e32 v97, v0
	v_mov_b32_e32 v98, v0
	v_mov_b32_e32 v99, v0
	v_mov_b32_e32 v100, v0
	v_mov_b32_e32 v101, v0
	v_mov_b32_e32 v102, v0
	v_mov_b32_e32 v103, v0
	v_mov_b32_e32 v104, v0
	v_mov_b32_e32 v105, v0
	v_mov_b32_e32 v106, v0
	v_mov_b32_e32 v107, v0
	v_mov_b32_e32 v108, v0
	v_mov_b32_e32 v109, v0
	v_mov_b32_e32 v110, v0
	v_mov_b32_e32 v111, v0
	v_mov_b32_e32 v112, v0
	v_mov_b32_e32 v113, v0
	v_mov_b32_e32 v114, v0
	v_mov_b32_e32 v115, v0
	v_mov_b32_e32 v116, v0
	v_mov_b32_e32 v117, v0
	v_mov_b32_e32 v118, v0
	v_mov_b32_e32 v119, v0
	v_mov_b32_e32 v120, v0
	v_mov_b32_e32 v121, v0
	v_mov_b32_e32 v122, v0
	v_mov_b32_e32 v123, v0
	v_mov_b32_e32 v124, v0
	v_mov_b32_e32 v125, v0
	v_mov_b32_e32 v126, v0
	v_mov_b32_e32 v127, v0
	s_waitcnt vmcnt(0) lgkmcnt(0)
	v_readfirstlane_b32 vcc_lo, v135
	s_bitcmp1_b32 vcc_lo, 8
	s_cbranch_scc0 .Lprio_skip3
	s_setprio 1

.LBB0_331:
	v_add_u32_e32 v214, s1, v161
	v_add3_u32 v210, v214, v156, v157
	v_add3_u32 v226, v214, v158, v157
	ds_read_b128 v[150:153], v210 offset:32768
	ds_read_b128 v[210:213], v210 offset:36864
	ds_read_b128 v[214:217], v226
	ds_read_b128 v[218:221], v226 offset:4096
	ds_read_b128 v[222:225], v226 offset:8192
	ds_read_b128 v[226:229], v226 offset:12288
	s_waitcnt lgkmcnt(3)
	v_mfma_f32_32x32x16_bf16 v[112:127], v[150:153], v[214:217], v[112:127]
	s_waitcnt lgkmcnt(2)
	v_mfma_f32_32x32x16_bf16 v[96:111], v[150:153], v[218:221], v[96:111]
	s_waitcnt lgkmcnt(1)
	v_mfma_f32_32x32x16_bf16 v[48:63], v[150:153], v[222:225], v[48:63]
	s_waitcnt lgkmcnt(0)
	v_mfma_f32_32x32x16_bf16 v[32:47], v[150:153], v[226:229], v[32:47]
	v_mfma_f32_32x32x16_bf16 v[80:95], v[210:213], v[214:217], v[80:95]
	v_mfma_f32_32x32x16_bf16 v[64:79], v[210:213], v[218:221], v[64:79]
	v_mfma_f32_32x32x16_bf16 v[16:31], v[210:213], v[222:225], v[16:31]
	v_mfma_f32_32x32x16_bf16 v[0:15], v[210:213], v[226:229], v[0:15]
	s_waitcnt vmcnt(0)
	s_add_u32 s50, s50, 0x80
	s_addc_u32 s51, s51, 0
	s_cmpk_eq_i32 s50, 0x800
	s_waitcnt vmcnt(0)
	s_barrier
	s_cbranch_scc1 .LBB0_338
.LBB0_332:
	s_cmpk_lg_i32 s50, 0x780
	s_cselect_b64 s[52:53], -1, 0
	s_and_b32 s1, s0, 0x10000
	s_add_i32 s1, s1, 0
	v_add_u32_e32 v150, s1, v155
	v_add3_u32 v151, v150, v156, v157
	v_add3_u32 v150, v150, v158, v157
	ds_read_b128 v[210:213], v151 offset:32768
	ds_read_b128 v[214:217], v151 offset:36864
	ds_read_b128 v[218:221], v150
	ds_read_b128 v[222:225], v150 offset:4096
	ds_read_b128 v[226:229], v150 offset:8192
	ds_read_b128 v[230:233], v150 offset:12288
	s_add_i32 s0, s0, 0x10000
	s_and_b32 s20, s0, 0x10000
	v_lshl_add_u64 v[152:153], v[148:149], 0, s[50:51]
	s_cmpk_eq_i32 s50, 0x780
	s_waitcnt lgkmcnt(3)
	v_mfma_f32_32x32x16_bf16 v[112:127], v[210:213], v[218:221], v[112:127]
	s_waitcnt lgkmcnt(2)
	v_mfma_f32_32x32x16_bf16 v[96:111], v[210:213], v[222:225], v[96:111]
	s_waitcnt lgkmcnt(1)
	v_mfma_f32_32x32x16_bf16 v[48:63], v[210:213], v[226:229], v[48:63]
	s_waitcnt lgkmcnt(0)
	v_mfma_f32_32x32x16_bf16 v[32:47], v[210:213], v[230:233], v[32:47]
	v_mfma_f32_32x32x16_bf16 v[80:95], v[214:217], v[218:221], v[80:95]
	v_mfma_f32_32x32x16_bf16 v[64:79], v[214:217], v[222:225], v[64:79]
	v_mfma_f32_32x32x16_bf16 v[16:31], v[214:217], v[226:229], v[16:31]
	v_mfma_f32_32x32x16_bf16 v[0:15], v[214:217], v[230:233], v[0:15]
	v_add_u32_e32 v210, s20, v154
	s_cbranch_scc1 .LBB0_334
	s_mov_b64 s[20:21], 0x35fac080
	v_lshl_add_u64 v[150:151], v[152:153], 0, s[20:21]
	s_mov_b64 s[20:21], 0x35f8c080
	v_lshl_add_u64 v[212:213], v[152:153], 0, s[20:21]
	s_mov_b64 s[20:21], 0x35f6c080
	v_lshl_add_u64 v[214:215], v[152:153], 0, s[20:21]
	v_readfirstlane_b32 s20, v210
	v_add_u32_e32 v211, 0x2000, v210
	s_mov_b32 m0, s20
	v_readfirstlane_b32 s20, v211
	v_add_u32_e32 v211, 0x4000, v210
	global_load_lds_dwordx4 v[214:215], off
	s_mov_b32 m0, s20
	v_readfirstlane_b32 s20, v211
	global_load_lds_dwordx4 v[212:213], off
	s_mov_b32 m0, s20
	s_nop 0
	global_load_lds_dwordx4 v[150:151], off
.LBB0_334:
	v_lshl_add_u64 v[150:151], v[146:147], 0, s[50:51]
	v_add_u32_e32 v211, s1, v159
	v_add3_u32 v216, v211, v156, v157
	v_add3_u32 v211, v211, v158, v157
	ds_read_b128 v[212:215], v216 offset:32768
	ds_read_b128 v[216:219], v216 offset:36864
	ds_read_b128 v[220:223], v211
	ds_read_b128 v[224:227], v211 offset:4096
	ds_read_b128 v[228:231], v211 offset:8192
	ds_read_b128 v[232:235], v211 offset:12288
	s_waitcnt lgkmcnt(3)
	v_mfma_f32_32x32x16_bf16 v[112:127], v[212:215], v[220:223], v[112:127]
	s_waitcnt lgkmcnt(2)
	v_mfma_f32_32x32x16_bf16 v[96:111], v[212:215], v[224:227], v[96:111]
	s_waitcnt lgkmcnt(1)
	v_mfma_f32_32x32x16_bf16 v[48:63], v[212:215], v[228:231], v[48:63]
	s_waitcnt lgkmcnt(0)
	v_mfma_f32_32x32x16_bf16 v[32:47], v[212:215], v[232:235], v[32:47]
	v_mfma_f32_32x32x16_bf16 v[80:95], v[216:219], v[220:223], v[80:95]
	v_mfma_f32_32x32x16_bf16 v[64:79], v[216:219], v[224:227], v[64:79]
	v_mfma_f32_32x32x16_bf16 v[16:31], v[216:219], v[228:231], v[16:31]
	v_mfma_f32_32x32x16_bf16 v[0:15], v[216:219], v[232:235], v[0:15]
	v_cndmask_b32_e64 v211, 0, 1, s[52:53]
	v_cmp_ne_u32_e64 s[38:39], 1, v211
	s_andn2_b64 vcc, exec, s[52:53]
	s_cbranch_vccnz .LBB0_336
	s_mov_b64 s[20:21], 0x35fcc080
	v_lshl_add_u64 v[152:153], v[152:153], 0, s[20:21]
	s_mov_b64 s[20:21], 0x1a00080
	v_lshl_add_u64 v[212:213], v[150:151], 0, s[20:21]
	s_mov_b64 s[20:21], 0x1a20080
	v_add_u32_e32 v211, 0x6000, v210
	v_lshl_add_u64 v[214:215], v[150:151], 0, s[20:21]
	v_readfirstlane_b32 s20, v211
	s_mov_b32 m0, s20
	s_nop 0
	global_load_lds_dwordx4 v[152:153], off
	v_add_u32_e32 v152, 0x8000, v210
	s_nop 0
	v_readfirstlane_b32 s20, v152
	v_add_u32_e32 v152, 0xa000, v210
	s_mov_b32 m0, s20
	v_readfirstlane_b32 s20, v152
	global_load_lds_dwordx4 v[212:213], off
	s_mov_b32 m0, s20
	s_nop 0
	global_load_lds_dwordx4 v[214:215], off
.LBB0_336:
	v_add_u32_e32 v152, s1, v160
	v_add3_u32 v153, v152, v156, v157
	v_add3_u32 v152, v152, v158, v157
	ds_read_b128 v[212:215], v153 offset:32768
	ds_read_b128 v[216:219], v153 offset:36864
	ds_read_b128 v[220:223], v152
	ds_read_b128 v[224:227], v152 offset:4096
	ds_read_b128 v[228:231], v152 offset:8192
	ds_read_b128 v[232:235], v152 offset:12288
	s_waitcnt lgkmcnt(3)
	v_mfma_f32_32x32x16_bf16 v[112:127], v[212:215], v[220:223], v[112:127]
	s_waitcnt lgkmcnt(2)
	v_mfma_f32_32x32x16_bf16 v[96:111], v[212:215], v[224:227], v[96:111]
	s_waitcnt lgkmcnt(1)
	v_mfma_f32_32x32x16_bf16 v[48:63], v[212:215], v[228:231], v[48:63]
	s_waitcnt lgkmcnt(0)
	v_mfma_f32_32x32x16_bf16 v[32:47], v[212:215], v[232:235], v[32:47]
	v_mfma_f32_32x32x16_bf16 v[80:95], v[216:219], v[220:223], v[80:95]
	v_mfma_f32_32x32x16_bf16 v[64:79], v[216:219], v[224:227], v[64:79]
	v_mfma_f32_32x32x16_bf16 v[16:31], v[216:219], v[228:231], v[16:31]
	v_mfma_f32_32x32x16_bf16 v[0:15], v[216:219], v[232:235], v[0:15]
	s_and_b64 vcc, exec, s[38:39]
	s_cbranch_vccnz .LBB0_331
	s_mov_b64 s[20:21], 0x1a40080
	v_lshl_add_u64 v[152:153], v[150:151], 0, s[20:21]
	s_mov_b64 s[20:21], 0x1a60080
	v_add_u32_e32 v211, 0xc000, v210
	v_lshl_add_u64 v[150:151], v[150:151], 0, s[20:21]
	v_readfirstlane_b32 s20, v211
	s_mov_b32 m0, s20
	s_nop 0
	global_load_lds_dwordx4 v[152:153], off
	v_add_u32_e32 v152, 0xe000, v210
	s_nop 0
	v_readfirstlane_b32 s20, v152
	s_mov_b32 m0, s20
	s_nop 0
	global_load_lds_dwordx4 v[150:151], off
	s_branch .LBB0_331
.LBB0_338:
	s_setprio 0
	s_andn2_b64 vcc, exec, s[48:49]
	s_cbranch_vccnz .LBB0_340
	s_lshl_b32 s0, s57, 8
	s_ashr_i32 s1, s0, 31
	s_lshl_b64 s[0:1], s[0:1], 11
	v_lshl_add_u64 v[146:147], v[130:131], 0, s[0:1]
	v_readfirstlane_b32 s0, v154
	s_mov_b32 m0, s0
	s_mov_b64 s[38:39], 0x20000
	v_readfirstlane_b32 s0, v209
	s_lshl_b32 s20, s56, 8
	global_load_lds_dwordx4 v[146:147], off
	v_lshl_add_u64 v[148:149], v[146:147], 0, s[38:39]
	s_mov_b32 m0, s0
	s_mov_b64 s[48:49], 0x40000
	v_readfirstlane_b32 s0, v208
	s_ashr_i32 s21, s20, 31
	global_load_lds_dwordx4 v[148:149], off
	v_lshl_add_u64 v[148:149], v[146:147], 0, s[48:49]
	s_mov_b32 m0, s0
	s_mov_b64 s[50:51], 0x60000
	v_readfirstlane_b32 s0, v207
	s_lshl_b64 s[20:21], s[20:21], 11
	global_load_lds_dwordx4 v[148:149], off
	v_lshl_add_u64 v[146:147], v[146:147], 0, s[50:51]
	s_mov_b32 m0, s0
	v_readfirstlane_b32 s0, v206
	global_load_lds_dwordx4 v[146:147], off
	v_lshl_add_u64 v[146:147], v[138:139], 0, s[20:21]
	s_mov_b32 m0, s0
	v_readfirstlane_b32 s0, v205
	global_load_lds_dwordx4 v[146:147], off
	v_lshl_add_u64 v[148:149], v[146:147], 0, s[38:39]
	s_mov_b32 m0, s0
	v_readfirstlane_b32 s0, v204
	global_load_lds_dwordx4 v[148:149], off
	v_lshl_add_u64 v[148:149], v[146:147], 0, s[48:49]
	s_mov_b32 m0, s0
	v_readfirstlane_b32 s0, v203
	global_load_lds_dwordx4 v[148:149], off
	v_lshl_add_u64 v[146:147], v[146:147], 0, s[50:51]
	s_mov_b32 m0, s0
	s_nop 0
	global_load_lds_dwordx4 v[146:147], off

.LBB0_372:
	s_waitcnt vmcnt(0)
	v_mov_b32_e32 v0, 0
	v_lshl_add_u64 v[128:129], v[142:143], 0, s[40:41]
	v_lshl_add_u64 v[130:131], v[142:143], 0, s[38:39]
	s_mov_b32 s0, 0
	s_mov_b64 s[40:41], 0
	v_mov_b32_e32 v1, v0
	v_mov_b32_e32 v2, v0
	v_mov_b32_e32 v3, v0
	v_mov_b32_e32 v4, v0
	v_mov_b32_e32 v5, v0
	v_mov_b32_e32 v6, v0
	v_mov_b32_e32 v7, v0
	v_mov_b32_e32 v8, v0
	v_mov_b32_e32 v9, v0
	v_mov_b32_e32 v10, v0
	v_mov_b32_e32 v11, v0
	v_mov_b32_e32 v12, v0
	v_mov_b32_e32 v13, v0
	v_mov_b32_e32 v14, v0
	v_mov_b32_e32 v15, v0
	v_mov_b32_e32 v16, v0
	v_mov_b32_e32 v17, v0
	v_mov_b32_e32 v18, v0
	v_mov_b32_e32 v19, v0
	v_mov_b32_e32 v20, v0
	v_mov_b32_e32 v21, v0
	v_mov_b32_e32 v22, v0
	v_mov_b32_e32 v23, v0
	v_mov_b32_e32 v24, v0
	v_mov_b32_e32 v25, v0
	v_mov_b32_e32 v26, v0
	v_mov_b32_e32 v27, v0
	v_mov_b32_e32 v28, v0
	v_mov_b32_e32 v29, v0
	v_mov_b32_e32 v30, v0
	v_mov_b32_e32 v31, v0
	v_mov_b32_e32 v64, v0
	v_mov_b32_e32 v65, v0
	v_mov_b32_e32 v66, v0
	v_mov_b32_e32 v67, v0
	v_mov_b32_e32 v68, v0
	v_mov_b32_e32 v69, v0
	v_mov_b32_e32 v70, v0
	v_mov_b32_e32 v71, v0
	v_mov_b32_e32 v72, v0
	v_mov_b32_e32 v73, v0
	v_mov_b32_e32 v74, v0
	v_mov_b32_e32 v75, v0
	v_mov_b32_e32 v76, v0
	v_mov_b32_e32 v77, v0
	v_mov_b32_e32 v78, v0
	v_mov_b32_e32 v79, v0
	v_mov_b32_e32 v80, v0
	v_mov_b32_e32 v81, v0
	v_mov_b32_e32 v82, v0
	v_mov_b32_e32 v83, v0
	v_mov_b32_e32 v84, v0
	v_mov_b32_e32 v85, v0
	v_mov_b32_e32 v86, v0
	v_mov_b32_e32 v87, v0
	v_mov_b32_e32 v88, v0
	v_mov_b32_e32 v89, v0
	v_mov_b32_e32 v90, v0
	v_mov_b32_e32 v91, v0
	v_mov_b32_e32 v92, v0
	v_mov_b32_e32 v93, v0
	v_mov_b32_e32 v94, v0
	v_mov_b32_e32 v95, v0
	v_mov_b32_e32 v32, v0
	v_mov_b32_e32 v33, v0
	v_mov_b32_e32 v34, v0
	v_mov_b32_e32 v35, v0
	v_mov_b32_e32 v36, v0
	v_mov_b32_e32 v37, v0
	v_mov_b32_e32 v38, v0
	v_mov_b32_e32 v39, v0
	v_mov_b32_e32 v40, v0
	v_mov_b32_e32 v41, v0
	v_mov_b32_e32 v42, v0
	v_mov_b32_e32 v43, v0
	v_mov_b32_e32 v44, v0
	v_mov_b32_e32 v45, v0
	v_mov_b32_e32 v46, v0
	v_mov_b32_e32 v47, v0
	v_mov_b32_e32 v48, v0
	v_mov_b32_e32 v49, v0
	v_mov_b32_e32 v50, v0
	v_mov_b32_e32 v51, v0
	v_mov_b32_e32 v52, v0
	v_mov_b32_e32 v53, v0
	v_mov_b32_e32 v54, v0
	v_mov_b32_e32 v55, v0
	v_mov_b32_e32 v56, v0
	v_mov_b32_e32 v57, v0
	v_mov_b32_e32 v58, v0
	v_mov_b32_e32 v59, v0
	v_mov_b32_e32 v60, v0
	v_mov_b32_e32 v61, v0
	v_mov_b32_e32 v62, v0
	v_mov_b32_e32 v63, v0
	v_mov_b32_e32 v96, v0
	v_mov_b32_e32 v97, v0
	v_mov_b32_e32 v98, v0
	v_mov_b32_e32 v99, v0
	v_mov_b32_e32 v100, v0
	v_mov_b32_e32 v101, v0
	v_mov_b32_e32 v102, v0
	v_mov_b32_e32 v103, v0
	v_mov_b32_e32 v104, v0
	v_mov_b32_e32 v105, v0
	v_mov_b32_e32 v106, v0
	v_mov_b32_e32 v107, v0
	v_mov_b32_e32 v108, v0
	v_mov_b32_e32 v109, v0
	v_mov_b32_e32 v110, v0
	v_mov_b32_e32 v111, v0
	v_mov_b32_e32 v112, v0
	v_mov_b32_e32 v113, v0
	v_mov_b32_e32 v114, v0
	v_mov_b32_e32 v115, v0
	v_mov_b32_e32 v116, v0
	v_mov_b32_e32 v117, v0
	v_mov_b32_e32 v118, v0
	v_mov_b32_e32 v119, v0
	v_mov_b32_e32 v120, v0
	v_mov_b32_e32 v121, v0
	v_mov_b32_e32 v122, v0
	v_mov_b32_e32 v123, v0
	v_mov_b32_e32 v124, v0
	v_mov_b32_e32 v125, v0
	v_mov_b32_e32 v126, v0
	v_mov_b32_e32 v127, v0
	s_waitcnt vmcnt(0) lgkmcnt(0)
	v_readfirstlane_b32 vcc_lo, v135
	s_bitcmp1_b32 vcc_lo, 8
	s_cbranch_scc0 .Lprio_skip4
	s_setprio 1

.LBB0_373:
	v_add_u32_e32 v222, s1, v199
	v_add3_u32 v218, v222, v158, v159
	v_add3_u32 v234, v222, v160, v159
	ds_read_b128 v[150:153], v218 offset:32768
	ds_read_b128 v[218:221], v218 offset:36864
	ds_read_b128 v[222:225], v234
	ds_read_b128 v[226:229], v234 offset:4096
	ds_read_b128 v[230:233], v234 offset:8192
	ds_read_b128 v[234:237], v234 offset:12288
	s_waitcnt lgkmcnt(3)
	v_mfma_f32_32x32x16_bf16 v[112:127], v[150:153], v[222:225], v[112:127]
	s_waitcnt lgkmcnt(2)
	v_mfma_f32_32x32x16_bf16 v[96:111], v[150:153], v[226:229], v[96:111]
	s_waitcnt lgkmcnt(1)
	v_mfma_f32_32x32x16_bf16 v[48:63], v[150:153], v[230:233], v[48:63]
	s_waitcnt lgkmcnt(0)
	v_mfma_f32_32x32x16_bf16 v[32:47], v[150:153], v[234:237], v[32:47]
	v_mfma_f32_32x32x16_bf16 v[80:95], v[218:221], v[222:225], v[80:95]
	v_mfma_f32_32x32x16_bf16 v[64:79], v[218:221], v[226:229], v[64:79]
	v_mfma_f32_32x32x16_bf16 v[16:31], v[218:221], v[230:233], v[16:31]
	v_mfma_f32_32x32x16_bf16 v[0:15], v[218:221], v[234:237], v[0:15]
	s_waitcnt vmcnt(0)
	s_add_u32 s40, s40, 0x80
	s_addc_u32 s41, s41, 0
	s_cmpk_eq_i32 s40, 0x800
	s_waitcnt vmcnt(0)
	s_barrier
	s_cbranch_scc1 .LBB0_380
.LBB0_374:
	s_cmpk_lg_i32 s40, 0x780
	s_cselect_b64 s[42:43], -1, 0
	s_and_b32 s1, s0, 0x10000
	s_add_i32 s1, s1, 0
	v_add_u32_e32 v150, s1, v157
	v_add3_u32 v151, v150, v158, v159
	v_add3_u32 v150, v150, v160, v159
	ds_read_b128 v[218:221], v151 offset:32768
	ds_read_b128 v[222:225], v151 offset:36864
	ds_read_b128 v[226:229], v150
	ds_read_b128 v[230:233], v150 offset:4096
	ds_read_b128 v[234:237], v150 offset:8192
	ds_read_b128 v[238:241], v150 offset:12288
	s_add_i32 s0, s0, 0x10000
	s_and_b32 s20, s0, 0x10000
	v_lshl_add_u64 v[152:153], v[130:131], 0, s[40:41]
	s_cmpk_eq_i32 s40, 0x780
	s_waitcnt lgkmcnt(3)
	v_mfma_f32_32x32x16_bf16 v[112:127], v[218:221], v[226:229], v[112:127]
	s_waitcnt lgkmcnt(2)
	v_mfma_f32_32x32x16_bf16 v[96:111], v[218:221], v[230:233], v[96:111]
	s_waitcnt lgkmcnt(1)
	v_mfma_f32_32x32x16_bf16 v[48:63], v[218:221], v[234:237], v[48:63]
	s_waitcnt lgkmcnt(0)
	v_mfma_f32_32x32x16_bf16 v[32:47], v[218:221], v[238:241], v[32:47]
	v_mfma_f32_32x32x16_bf16 v[80:95], v[222:225], v[226:229], v[80:95]
	v_mfma_f32_32x32x16_bf16 v[64:79], v[222:225], v[230:233], v[64:79]
	v_mfma_f32_32x32x16_bf16 v[16:31], v[222:225], v[234:237], v[16:31]
	v_mfma_f32_32x32x16_bf16 v[0:15], v[222:225], v[238:241], v[0:15]
	v_add_u32_e32 v218, s20, v156
	s_cbranch_scc1 .LBB0_376
	s_mov_b64 s[20:21], 0x67ac080
	v_lshl_add_u64 v[150:151], v[152:153], 0, s[20:21]
	s_mov_b64 s[20:21], 0x678c080
	v_lshl_add_u64 v[220:221], v[152:153], 0, s[20:21]
	s_mov_b64 s[20:21], 0x676c080
	v_lshl_add_u64 v[222:223], v[152:153], 0, s[20:21]
	v_readfirstlane_b32 s20, v218
	v_add_u32_e32 v219, 0x2000, v218
	s_mov_b32 m0, s20
	v_readfirstlane_b32 s20, v219
	v_add_u32_e32 v219, 0x4000, v218
	global_load_lds_dwordx4 v[222:223], off
	s_mov_b32 m0, s20
	v_readfirstlane_b32 s20, v219
	global_load_lds_dwordx4 v[220:221], off
	s_mov_b32 m0, s20
	s_nop 0
	global_load_lds_dwordx4 v[150:151], off
.LBB0_376:
	v_lshl_add_u64 v[150:151], v[128:129], 0, s[40:41]
	v_add_u32_e32 v219, s1, v161
	v_add3_u32 v224, v219, v158, v159
	v_add3_u32 v219, v219, v160, v159
	ds_read_b128 v[220:223], v224 offset:32768
	ds_read_b128 v[224:227], v224 offset:36864
	ds_read_b128 v[228:231], v219
	ds_read_b128 v[232:235], v219 offset:4096
	ds_read_b128 v[236:239], v219 offset:8192
	ds_read_b128 v[240:243], v219 offset:12288
	s_waitcnt lgkmcnt(3)
	v_mfma_f32_32x32x16_bf16 v[112:127], v[220:223], v[228:231], v[112:127]
	s_waitcnt lgkmcnt(2)
	v_mfma_f32_32x32x16_bf16 v[96:111], v[220:223], v[232:235], v[96:111]
	s_waitcnt lgkmcnt(1)
	v_mfma_f32_32x32x16_bf16 v[48:63], v[220:223], v[236:239], v[48:63]
	s_waitcnt lgkmcnt(0)
	v_mfma_f32_32x32x16_bf16 v[32:47], v[220:223], v[240:243], v[32:47]
	v_mfma_f32_32x32x16_bf16 v[80:95], v[224:227], v[228:231], v[80:95]
	v_mfma_f32_32x32x16_bf16 v[64:79], v[224:227], v[232:235], v[64:79]
	v_mfma_f32_32x32x16_bf16 v[16:31], v[224:227], v[236:239], v[16:31]
	v_mfma_f32_32x32x16_bf16 v[0:15], v[224:227], v[240:243], v[0:15]
	v_cndmask_b32_e64 v219, 0, 1, s[42:43]
	v_cmp_ne_u32_e64 s[38:39], 1, v219
	s_andn2_b64 vcc, exec, s[42:43]
	s_cbranch_vccnz .LBB0_378
	s_mov_b64 s[20:21], 0x67cc080
	v_lshl_add_u64 v[152:153], v[152:153], 0, s[20:21]
	s_mov_b64 s[20:21], 0x80
	v_lshl_add_u64 v[220:221], v[150:151], 0, s[20:21]
	s_mov_b64 s[20:21], 0x20080
	v_add_u32_e32 v219, 0x6000, v218
	v_lshl_add_u64 v[222:223], v[150:151], 0, s[20:21]
	v_readfirstlane_b32 s20, v219
	s_mov_b32 m0, s20
	s_nop 0
	global_load_lds_dwordx4 v[152:153], off
	v_add_u32_e32 v152, 0x8000, v218
	s_nop 0
	v_readfirstlane_b32 s20, v152
	v_add_u32_e32 v152, 0xa000, v218
	s_mov_b32 m0, s20
	v_readfirstlane_b32 s20, v152
	global_load_lds_dwordx4 v[220:221], off
	s_mov_b32 m0, s20
	s_nop 0
	global_load_lds_dwordx4 v[222:223], off
.LBB0_378:
	v_add_u32_e32 v152, s1, v198
	v_add3_u32 v153, v152, v158, v159
	v_add3_u32 v152, v152, v160, v159
	ds_read_b128 v[220:223], v153 offset:32768
	ds_read_b128 v[224:227], v153 offset:36864
	ds_read_b128 v[228:231], v152
	ds_read_b128 v[232:235], v152 offset:4096
	ds_read_b128 v[236:239], v152 offset:8192
	ds_read_b128 v[240:243], v152 offset:12288
	s_waitcnt lgkmcnt(3)
	v_mfma_f32_32x32x16_bf16 v[112:127], v[220:223], v[228:231], v[112:127]
	s_waitcnt lgkmcnt(2)
	v_mfma_f32_32x32x16_bf16 v[96:111], v[220:223], v[232:235], v[96:111]
	s_waitcnt lgkmcnt(1)
	v_mfma_f32_32x32x16_bf16 v[48:63], v[220:223], v[236:239], v[48:63]
	s_waitcnt lgkmcnt(0)
	v_mfma_f32_32x32x16_bf16 v[32:47], v[220:223], v[240:243], v[32:47]
	v_mfma_f32_32x32x16_bf16 v[80:95], v[224:227], v[228:231], v[80:95]
	v_mfma_f32_32x32x16_bf16 v[64:79], v[224:227], v[232:235], v[64:79]
	v_mfma_f32_32x32x16_bf16 v[16:31], v[224:227], v[236:239], v[16:31]
	v_mfma_f32_32x32x16_bf16 v[0:15], v[224:227], v[240:243], v[0:15]
	s_and_b64 vcc, exec, s[38:39]
	s_cbranch_vccnz .LBB0_373
	s_mov_b64 s[20:21], 0x40080
	v_lshl_add_u64 v[152:153], v[150:151], 0, s[20:21]
	s_mov_b64 s[20:21], 0x60080
	v_add_u32_e32 v219, 0xc000, v218
	v_lshl_add_u64 v[150:151], v[150:151], 0, s[20:21]
	v_readfirstlane_b32 s20, v219
	s_mov_b32 m0, s20
	s_nop 0
	global_load_lds_dwordx4 v[152:153], off
	v_add_u32_e32 v152, 0xe000, v218
	s_nop 0
	v_readfirstlane_b32 s20, v152
	s_mov_b32 m0, s20
	s_nop 0
	global_load_lds_dwordx4 v[150:151], off
	s_branch .LBB0_373
.LBB0_380:
	s_setprio 0
	s_andn2_b64 vcc, exec, s[30:31]
	s_cbranch_vccnz .LBB0_382
	s_lshl_b32 s0, s64, 8
	s_ashr_i32 s1, s0, 31
	s_lshl_b64 s[0:1], s[0:1], 11
	v_lshl_add_u64 v[128:129], v[140:141], 0, s[0:1]
	v_readfirstlane_b32 s0, v156
	s_mov_b32 m0, s0
	s_mov_b64 s[30:31], 0x20000
	v_readfirstlane_b32 s0, v217
	s_lshl_b32 s20, s65, 8
	global_load_lds_dwordx4 v[128:129], off
	v_lshl_add_u64 v[130:131], v[128:129], 0, s[30:31]
	s_mov_b32 m0, s0
	s_mov_b64 s[38:39], 0x40000
	v_readfirstlane_b32 s0, v216
	s_ashr_i32 s21, s20, 31
	global_load_lds_dwordx4 v[130:131], off
	v_lshl_add_u64 v[130:131], v[128:129], 0, s[38:39]
	s_mov_b32 m0, s0
	s_mov_b64 s[40:41], 0x60000
	v_readfirstlane_b32 s0, v215
	s_lshl_b64 s[20:21], s[20:21], 11
	global_load_lds_dwordx4 v[130:131], off
	v_lshl_add_u64 v[128:129], v[128:129], 0, s[40:41]
	s_mov_b32 m0, s0
	v_readfirstlane_b32 s0, v155
	global_load_lds_dwordx4 v[128:129], off
	v_lshl_add_u64 v[128:129], v[142:143], 0, s[20:21]
	s_mov_b32 m0, s0
	v_readfirstlane_b32 s0, v154
	global_load_lds_dwordx4 v[128:129], off
	v_lshl_add_u64 v[130:131], v[128:129], 0, s[30:31]
	s_mov_b32 m0, s0
	v_readfirstlane_b32 s0, v149
	global_load_lds_dwordx4 v[130:131], off
	v_lshl_add_u64 v[130:131], v[128:129], 0, s[38:39]
	s_mov_b32 m0, s0
	v_readfirstlane_b32 s0, v132
	global_load_lds_dwordx4 v[130:131], off
	v_lshl_add_u64 v[128:129], v[128:129], 0, s[40:41]
	s_mov_b32 m0, s0
	s_nop 0
	global_load_lds_dwordx4 v[128:129], off
